# v71 + nt hint on other once-read streams: P0 weight/x loads, out-proj residual loads, attention epilogue gate loads
# speedup vs baseline: 1.0101x; 1.0068x over previous
.LBB0_18:
	v_add_u32_e32 v36, s14, v6
	s_ashr_i32 s17, s16, 31
	v_add_u32_e32 v37, s8, v6
	s_ashr_i32 s11, s10, 31
	v_lshl_add_u64 v[52:53], s[16:17], 2, v[4:5]
	v_lshl_add_u64 v[60:61], s[10:11], 2, v[4:5]
	v_add_u32_e32 v38, 16, v36
	v_add_u32_e32 v39, 16, v37
	v_add_u32_e32 v40, 32, v36
	v_add_u32_e32 v48, 32, v37
	v_mad_i64_i32 v[32:33], s[24:25], v36, s21, v[52:53]
	v_add_u32_e32 v58, 48, v36
	v_mad_i64_i32 v[44:45], s[24:25], v37, s21, v[60:61]
	v_mad_i64_i32 v[46:47], s[24:25], v38, s21, v[52:53]
	v_mad_i64_i32 v[54:55], s[24:25], v39, s21, v[60:61]
	v_mad_i64_i32 v[56:57], s[24:25], v40, s21, v[52:53]
	v_mad_i64_i32 v[62:63], s[24:25], v48, s21, v[60:61]
	global_load_dwordx4 v[32:35], v[32:33], off nt
	v_add_u32_e32 v66, 48, v37
	global_load_dwordx4 v[36:39], v[44:45], off nt
	global_load_dwordx4 v[40:43], v[46:47], off nt
	s_nop 0
	global_load_dwordx4 v[44:47], v[54:55], off nt
	global_load_dwordx4 v[48:51], v[56:57], off nt
	v_mad_i64_i32 v[64:65], s[24:25], v58, s21, v[52:53]
	global_load_dwordx4 v[52:55], v[62:63], off nt
	global_load_dwordx4 v[56:59], v[64:65], off nt
	v_mad_i64_i32 v[60:61], s[24:25], v66, s21, v[60:61]
	global_load_dwordx4 v[60:63], v[60:61], off nt
	s_ashr_i32 s15, s14, 31
	s_and_b64 vcc, exec, s[4:5]
	s_waitcnt vmcnt(7)
	ds_write2_b32 v10, v32, v33 offset1:1
	ds_write2_b32 v10, v34, v35 offset0:2 offset1:3
	s_waitcnt vmcnt(6)
	ds_write2_b32 v11, v36, v37 offset1:1
	ds_write2_b32 v12, v38, v39 offset1:1
	s_waitcnt vmcnt(5)
	ds_write2_b32 v13, v40, v41 offset1:1
	ds_write2_b32 v14, v42, v43 offset1:1
	s_waitcnt vmcnt(4)
	ds_write2_b32 v15, v44, v45 offset1:1
	ds_write2_b32 v16, v46, v47 offset1:1
	s_waitcnt vmcnt(3)
	ds_write2_b32 v17, v48, v49 offset1:1
	ds_write2_b32 v18, v50, v51 offset1:1
	s_waitcnt vmcnt(2)
	ds_write2_b32 v19, v52, v53 offset1:1
	ds_write2_b32 v20, v54, v55 offset1:1
	s_waitcnt vmcnt(1)
	ds_write2_b32 v21, v56, v57 offset1:1
	ds_write2_b32 v22, v58, v59 offset1:1
	s_waitcnt vmcnt(0)
	ds_write2_b32 v23, v60, v61 offset1:1
	ds_write2_b32 v24, v62, v63 offset1:1
	s_waitcnt lgkmcnt(0)
	s_barrier
	ds_read2_b32 v[32:33], v9 offset1:129
	s_waitcnt lgkmcnt(0)
	v_cvt_pk_bf16_f32 v32, v32, v33
	ds_read2_b32 v[34:35], v25 offset0:2 offset1:131
	v_add_u32_e32 v40, s16, v7
	s_waitcnt lgkmcnt(0)
	v_cvt_pk_bf16_f32 v33, v34, v35
	ds_read2_b32 v[34:35], v26 offset0:4 offset1:133
	v_ashrrev_i32_e32 v41, 31, v40
	s_waitcnt lgkmcnt(0)
	v_cvt_pk_bf16_f32 v34, v34, v35
	ds_read2_b32 v[36:37], v27 offset0:6 offset1:135
	v_lshlrev_b64 v[40:41], 12, v[40:41]
	s_waitcnt lgkmcnt(0)
	v_cvt_pk_bf16_f32 v35, v36, v37
	ds_read2_b32 v[36:37], v28 offset0:8 offset1:137
	v_lshl_add_u64 v[40:41], s[6:7], 0, v[40:41]
	s_waitcnt lgkmcnt(0)
	v_cvt_pk_bf16_f32 v36, v36, v37
	ds_read2_b32 v[38:39], v29 offset0:10 offset1:139
	v_lshl_add_u64 v[40:41], s[14:15], 1, v[40:41]
	s_waitcnt lgkmcnt(0)
	v_cvt_pk_bf16_f32 v37, v38, v39
	ds_read2_b32 v[38:39], v30 offset0:12 offset1:141
	v_lshl_add_u64 v[40:41], v[40:41], 0, v[2:3]
	s_waitcnt lgkmcnt(0)
	v_cvt_pk_bf16_f32 v38, v38, v39
	ds_read2_b32 v[42:43], v31 offset0:14 offset1:143
	s_waitcnt lgkmcnt(0)
	v_cvt_pk_bf16_f32 v39, v42, v43
	global_store_dwordx4 v[40:41], v[32:35], off
	global_store_dwordx4 v[40:41], v[36:39], off offset:16
	s_cbranch_vccnz .LBB0_13
	v_add_u32_e32 v32, 0x8000, v9
	ds_read2_b32 v[32:33], v32 offset0:64 offset1:193
	v_add_u32_e32 v34, 0x8400, v9
	s_waitcnt lgkmcnt(0)
	v_cvt_pk_bf16_f32 v32, v32, v33
	ds_read2_b32 v[34:35], v34 offset0:66 offset1:195
	v_add_u32_e32 v36, 0x8800, v9
	s_waitcnt lgkmcnt(0)
	v_cvt_pk_bf16_f32 v33, v34, v35
	ds_read2_b32 v[34:35], v36 offset0:68 offset1:197
	v_add_u32_e32 v36, 0x8c00, v9
	s_waitcnt lgkmcnt(0)
	v_cvt_pk_bf16_f32 v34, v34, v35
	ds_read2_b32 v[36:37], v36 offset0:70 offset1:199
	v_add_u32_e32 v38, 0x9000, v9
	s_waitcnt lgkmcnt(0)
	v_cvt_pk_bf16_f32 v35, v36, v37
	ds_read2_b32 v[36:37], v38 offset0:72 offset1:201
	v_add_u32_e32 v38, 0x9400, v9
	s_waitcnt lgkmcnt(0)
	v_cvt_pk_bf16_f32 v36, v36, v37
	ds_read2_b32 v[38:39], v38 offset0:74 offset1:203
	v_add_u32_e32 v40, 0x9800, v9
	s_waitcnt lgkmcnt(0)
	v_cvt_pk_bf16_f32 v37, v38, v39
	ds_read2_b32 v[38:39], v40 offset0:76 offset1:205
	v_add_u32_e32 v40, s10, v7
	v_ashrrev_i32_e32 v41, 31, v40
	v_lshlrev_b64 v[40:41], 12, v[40:41]
	s_ashr_i32 s9, s8, 31
	v_lshl_add_u64 v[40:41], s[6:7], 0, v[40:41]
	v_lshl_add_u64 v[40:41], s[8:9], 1, v[40:41]
	v_add_u32_e32 v42, 0x9c00, v9
	v_lshl_add_u64 v[40:41], v[40:41], 0, v[2:3]
	s_waitcnt lgkmcnt(0)
	v_cvt_pk_bf16_f32 v38, v38, v39
	ds_read2_b32 v[42:43], v42 offset0:78 offset1:207
	s_waitcnt lgkmcnt(0)
	v_cvt_pk_bf16_f32 v39, v42, v43
	global_store_dwordx4 v[40:41], v[32:35], off
	global_store_dwordx4 v[40:41], v[36:39], off offset:16
	s_branch .LBB0_13

.LBB0_22:
	s_ashr_i32 s9, s8, 31
	s_bfe_u32 s10, s14, 0x30001
	s_lshl_b64 s[8:9], s[8:9], 3
	s_add_u32 s8, s96, s8
	s_addc_u32 s9, s97, s9
	s_load_dwordx2 s[8:9], s[8:9], 0x0
	s_ashr_i32 s11, s14, 1
	s_and_b32 s11, s11, -8
	s_or_b32 s26, s11, s10
	s_ashr_i32 s27, s26, 31
	s_mov_b32 s11, 0
	s_lshl_b64 s[26:27], s[26:27], 18
	v_mbcnt_lo_u32_b32 v2, -1, 0
	v_mbcnt_hi_u32_b32 v2, -1, v2
	s_waitcnt lgkmcnt(0)
	s_add_u32 s8, s8, s26
	v_add_u32_e32 v9, s33, v2
	v_ashrrev_i32_e32 v22, 5, v9
	v_lshlrev_b32_e32 v23, 4, v2
	s_addc_u32 s9, s9, s27
	v_and_b32_e32 v2, 0x1f0, v23
	v_add_u32_e32 v6, s17, v22
	v_lshl_add_u64 v[4:5], s[8:9], 0, v[2:3]
	v_ashrrev_i32_e32 v7, 31, v6
	v_lshl_add_u64 v[4:5], v[4:5], 0, s[4:5]
	v_lshlrev_b64 v[6:7], 10, v[6:7]
	v_lshl_add_u64 v[18:19], v[4:5], 0, v[6:7]
	global_load_dwordx4 v[4:7], v[18:19], off nt
	v_add_co_u32_e32 v10, vcc, s21, v18
	v_and_b32_e32 v23, 48, v23
	s_nop 0
	v_addc_co_u32_e32 v11, vcc, 0, v19, vcc
	global_load_dwordx4 v[10:13], v[10:11], off nt
	v_add_co_u32_e32 v14, vcc, s22, v18
	v_and_b32_e32 v24, -4, v9
	s_nop 0
	v_addc_co_u32_e32 v15, vcc, 0, v19, vcc
	global_load_dwordx4 v[14:17], v[14:15], off nt
	v_add_co_u32_e32 v18, vcc, s23, v18
	v_mul_lo_u32 v22, v22, s20
	s_nop 0
	v_addc_co_u32_e32 v19, vcc, 0, v19, vcc
	global_load_dwordx4 v[18:21], v[18:19], off nt
	v_mul_u32_u24_e32 v25, 0x204, v23
	v_add3_u32 v2, 0, v2, v22
	v_add3_u32 v22, 0, v25, v24
	v_add_u32_e32 v24, 0x8100, v2
	v_add_u32_e32 v25, 0x8108, v2
	v_add_u32_e32 v26, 0x2040, v2
	v_add_u32_e32 v27, 0x2048, v2
	v_add_u32_e32 v28, 0xa140, v2
	v_add_u32_e32 v29, 0xa148, v2
	v_add_u32_e32 v30, 0x4080, v2
	v_add_u32_e32 v31, 0x4088, v2
	v_add_u32_e32 v32, 0xc180, v2
	v_add_u32_e32 v33, 0xc188, v2
	v_add_u32_e32 v34, 0x60c0, v2
	v_add_u32_e32 v35, 0x60c8, v2
	v_add_u32_e32 v36, 0xe1c0, v2
	v_add_u32_e32 v37, 0xe1c8, v2
	s_ashr_i32 s8, s11, 31
	s_add_u32 s11, s15, s11
	s_waitcnt vmcnt(3)
	ds_write2_b32 v2, v4, v5 offset1:1
	ds_write2_b32 v2, v6, v7 offset0:2 offset1:3
	ds_write2_b32 v24, v4, v5 offset1:1
	ds_write2_b32 v25, v6, v7 offset1:1
	s_waitcnt vmcnt(2)
	ds_write2_b32 v26, v10, v11 offset1:1
	ds_write2_b32 v27, v12, v13 offset1:1
	ds_write2_b32 v28, v10, v11 offset1:1
	ds_write2_b32 v29, v12, v13 offset1:1
	s_waitcnt vmcnt(1)
	ds_write2_b32 v30, v14, v15 offset1:1
	ds_write2_b32 v31, v16, v17 offset1:1
	ds_write2_b32 v32, v14, v15 offset1:1
	ds_write2_b32 v33, v16, v17 offset1:1
	s_waitcnt vmcnt(0)
	ds_write2_b32 v34, v18, v19 offset1:1
	ds_write2_b32 v35, v20, v21 offset1:1
	ds_write2_b32 v36, v18, v19 offset1:1
	ds_write2_b32 v37, v20, v21 offset1:1
	s_waitcnt lgkmcnt(0)
	s_barrier
	ds_read2_b32 v[4:5], v22 offset1:129
	v_ashrrev_i32_e32 v2, 2, v9
	s_waitcnt lgkmcnt(0)
	v_cvt_pk_bf16_f32 v4, v4, v5
	v_and_b32_e32 v5, 0x7f, v2
	v_lshl_or_b32 v9, s25, 7, v5
	s_addc_u32 s25, s16, s8
	s_and_b32 s8, s14, -16
	s_lshl_b32 s9, s10, 1
	v_add_u32_e32 v6, 0x400, v22
	s_or_b32 s8, s9, s8
	ds_read2_b32 v[6:7], v6 offset0:2 offset1:131
	v_add_lshl_u32 v2, v2, s18, 1
	v_add_u32_e32 v10, 0x800, v22
	s_ashr_i32 s9, s8, 31
	s_waitcnt lgkmcnt(0)
	v_cvt_pk_bf16_f32 v5, v6, v7
	ds_read2_b32 v[6:7], v10 offset0:4 offset1:133
	v_add_u32_e32 v10, 0xc00, v22
	v_and_or_b32 v12, v2, s24, v9
	s_lshl_b64 s[8:9], s[8:9], 17
	v_add_u32_e32 v14, 0x1000, v22
	s_waitcnt lgkmcnt(0)
	v_cvt_pk_bf16_f32 v6, v6, v7
	ds_read2_b32 v[10:11], v10 offset0:6 offset1:135
	v_ashrrev_i32_e32 v13, 31, v12
	s_add_u32 s8, s11, s8
	s_waitcnt lgkmcnt(0)
	v_cvt_pk_bf16_f32 v7, v10, v11
	ds_read2_b32 v[10:11], v14 offset0:8 offset1:137
	v_lshlrev_b64 v[14:15], 9, v[12:13]
	s_addc_u32 s9, s25, s9
	v_add_u32_e32 v16, 0x1400, v22
	v_lshl_add_u64 v[14:15], s[8:9], 0, v[14:15]
	v_add_u32_e32 v17, 0x1800, v22
	v_lshlrev_b32_e32 v2, 1, v23
	s_waitcnt lgkmcnt(0)
	v_cvt_pk_bf16_f32 v10, v10, v11
	ds_read2_b32 v[12:13], v16 offset0:10 offset1:139
	s_add_i32 s14, s14, s19
	v_lshl_add_u64 v[14:15], v[14:15], 0, s[6:7]
	v_add_u32_e32 v18, 0x1c00, v22
	s_waitcnt lgkmcnt(0)
	v_cvt_pk_bf16_f32 v11, v12, v13
	ds_read2_b32 v[12:13], v17 offset0:12 offset1:141
	s_cmp_gt_i32 s14, 31
	v_lshl_add_u64 v[14:15], v[14:15], 0, v[2:3]
	s_waitcnt lgkmcnt(0)
	v_cvt_pk_bf16_f32 v12, v12, v13
	ds_read2_b32 v[16:17], v18 offset0:14 offset1:143
	s_waitcnt lgkmcnt(0)
	v_cvt_pk_bf16_f32 v13, v16, v17
	global_store_dwordx4 v[14:15], v[4:7], off
	global_store_dwordx4 v[14:15], v[10:13], off offset:16
	s_barrier
	s_cbranch_scc1 .LBB0_27

.LBB0_56:
	global_load_dwordx4 v[32:35], v[22:23], off offset:-4096 nt
	global_load_dwordx4 v[36:39], v[22:23], off offset:-3072 nt
	global_load_dwordx4 v[40:43], v[22:23], off nt
	global_load_dwordx4 v[44:47], v[22:23], off offset:1024 nt
	global_load_dwordx4 v[48:51], v[22:23], off offset:2048 nt
	global_load_dwordx4 v[6:9], v[22:23], off offset:3072 nt
	global_load_dwordx4 v[52:55], v[22:23], off offset:-2048 nt
	global_load_dwordx4 v[56:59], v[22:23], off offset:-1024 nt
	v_add_u32_e32 v10, s6, v10
	v_lshl_add_u64 v[22:23], v[22:23], 0, s[8:9]
	s_waitcnt vmcnt(7)
	v_mul_f32_e32 v76, v33, v33
	s_waitcnt vmcnt(6)
	v_mul_f32_e32 v77, v37, v37
	v_fmac_f32_e32 v76, v32, v32
	v_fmac_f32_e32 v77, v36, v36
	s_waitcnt vmcnt(5)
	v_mov_b32_e32 v62, v41
	s_waitcnt vmcnt(4)
	v_mov_b32_e32 v63, v45
	s_waitcnt vmcnt(1)
	v_mul_f32_e32 v78, v53, v53
	v_mov_b32_e32 v66, v49
	v_mov_b32_e32 v67, v7
	s_waitcnt vmcnt(0)
	v_mul_f32_e32 v79, v57, v57
	v_fmac_f32_e32 v78, v52, v52
	v_fmac_f32_e32 v76, v34, v34
	v_fmac_f32_e32 v77, v38, v38
	v_mov_b32_e32 v60, v40
	v_mov_b32_e32 v61, v44
	v_mov_b32_e32 v64, v48
	v_mov_b32_e32 v65, v6
	v_pk_mul_f32 v[62:63], v[62:63], v[62:63]
	v_pk_mul_f32 v[66:67], v[66:67], v[66:67]
	v_fmac_f32_e32 v79, v56, v56
	v_fmac_f32_e32 v78, v54, v54
	v_fmac_f32_e32 v76, v35, v35
	v_fmac_f32_e32 v77, v39, v39
	v_mov_b32_e32 v68, v42
	v_mov_b32_e32 v69, v46
	v_pk_fma_f32 v[60:61], v[60:61], v[60:61], v[62:63]
	v_pk_fma_f32 v[62:63], v[64:65], v[64:65], v[66:67]
	v_fmac_f32_e32 v79, v58, v58
	v_fmac_f32_e32 v78, v55, v55
	v_add_f32_e32 v64, v76, v77
	v_mov_b32_e32 v72, v43
	v_mov_b32_e32 v73, v47
	v_pk_fma_f32 v[60:61], v[68:69], v[68:69], v[60:61]
	v_fmac_f32_e32 v79, v59, v59
	v_add_f32_e32 v64, v64, v78
	v_mov_b32_e32 v70, v50
	v_mov_b32_e32 v71, v8
	v_pk_fma_f32 v[60:61], v[72:73], v[72:73], v[60:61]
	v_add_f32_e32 v64, v64, v79
	v_mov_b32_e32 v74, v51
	v_mov_b32_e32 v75, v9
	v_pk_fma_f32 v[62:63], v[70:71], v[70:71], v[62:63]
	v_add_f32_e32 v60, v64, v60
	v_pk_fma_f32 v[62:63], v[74:75], v[74:75], v[62:63]
	v_add_f32_e32 v60, v60, v61
	v_add_f32_e32 v60, v60, v62
	v_add_f32_e32 v60, v60, v63
	ds_bpermute_b32 v61, v26, v60
	s_waitcnt lgkmcnt(0)
	v_add_f32_e32 v60, v60, v61
	ds_bpermute_b32 v61, v27, v60
	s_waitcnt lgkmcnt(0)
	v_add_f32_e32 v60, v60, v61
	ds_bpermute_b32 v61, v28, v60
	s_waitcnt lgkmcnt(0)
	v_add_f32_e32 v60, v60, v61
	ds_bpermute_b32 v61, v29, v60
	s_waitcnt lgkmcnt(0)
	v_add_f32_e32 v60, v60, v61
	ds_bpermute_b32 v61, v30, v60
	s_waitcnt lgkmcnt(0)
	v_add_f32_e32 v60, v60, v61
	ds_bpermute_b32 v61, v31, v60
	s_waitcnt lgkmcnt(0)
	v_add_f32_e32 v60, v60, v61
	v_fmamk_f32 v60, v60, 0x3a000000, v11
	v_mul_f32_e32 v61, 0x4b800000, v60
	v_cmp_gt_f32_e32 vcc, s7, v60
	s_nop 1
	v_cndmask_b32_e32 v60, v60, v61, vcc
	v_rsq_f32_e32 v60, v60
	s_nop 0
	v_mul_f32_e32 v61, 0x45800000, v60
	v_cndmask_b32_e32 v62, v60, v61, vcc
	v_mul_f32_e32 v32, v32, v62
	v_mul_f32_e32 v33, v33, v62
	v_mul_f32_e32 v34, v34, v62
	v_mul_f32_e32 v35, v35, v62
	v_mul_f32_e32 v32, v2, v32
	v_mul_f32_e32 v33, v3, v33
	v_mul_f32_e32 v34, v4, v34
	v_mul_f32_e32 v35, v5, v35
	v_cvt_pk_bf16_f32 v60, v32, v33
	v_cvt_pk_bf16_f32 v61, v34, v35
	global_load_dwordx4 v[32:35], v[12:13], off offset:1024 nt
	v_mul_f32_e32 v36, v36, v62
	v_mul_f32_e32 v37, v37, v62
	v_mul_f32_e32 v38, v38, v62
	v_mul_f32_e32 v39, v39, v62
	global_store_dwordx2 v[24:25], v[60:61], off offset:-2048
	v_mul_f32_e32 v6, v6, v62
	v_mul_f32_e32 v7, v7, v62
	v_cmp_lt_i32_e32 vcc, s16, v10
	v_mul_f32_e32 v8, v8, v62
	v_mul_f32_e32 v9, v9, v62
	s_or_b64 s[14:15], vcc, s[14:15]
	s_waitcnt vmcnt(1)
	v_mul_f32_e32 v32, v32, v36
	v_mul_f32_e32 v33, v33, v37
	v_mul_f32_e32 v34, v34, v38
	v_mul_f32_e32 v35, v35, v39
	v_cvt_pk_bf16_f32 v36, v32, v33
	v_cvt_pk_bf16_f32 v37, v34, v35
	global_load_dwordx4 v[32:35], v[12:13], off offset:2048 nt
	v_mul_f32_e32 v38, v52, v62
	v_mul_f32_e32 v39, v53, v62
	v_mul_f32_e32 v52, v54, v62
	v_mul_f32_e32 v53, v55, v62
	global_store_dwordx2 v[24:25], v[36:37], off offset:-1536
	s_waitcnt vmcnt(1)
	v_mul_f32_e32 v32, v32, v38
	v_mul_f32_e32 v33, v33, v39
	v_mul_f32_e32 v34, v34, v52
	v_mul_f32_e32 v35, v35, v53
	v_cvt_pk_bf16_f32 v36, v32, v33
	v_cvt_pk_bf16_f32 v37, v34, v35
	global_load_dwordx4 v[32:35], v[12:13], off offset:3072 nt
	v_mul_f32_e32 v38, v56, v62
	v_mul_f32_e32 v39, v57, v62
	v_mul_f32_e32 v52, v58, v62
	v_mul_f32_e32 v53, v59, v62
	global_store_dwordx2 v[24:25], v[36:37], off offset:-1024
	s_waitcnt vmcnt(1)
	v_mul_f32_e32 v32, v32, v38
	v_mul_f32_e32 v33, v33, v39
	v_mul_f32_e32 v34, v34, v52
	v_mul_f32_e32 v35, v35, v53
	v_cvt_pk_bf16_f32 v36, v32, v33
	v_cvt_pk_bf16_f32 v37, v34, v35
	global_load_dwordx4 v[32:35], v[14:15], off nt
	v_mul_f32_e32 v38, v40, v62
	v_mul_f32_e32 v39, v41, v62
	v_mul_f32_e32 v40, v42, v62
	v_mul_f32_e32 v41, v43, v62
	global_store_dwordx2 v[24:25], v[36:37], off offset:-512
	s_waitcnt vmcnt(1)
	v_mul_f32_e32 v32, v38, v32
	v_mul_f32_e32 v33, v39, v33
	v_mul_f32_e32 v34, v40, v34
	v_mul_f32_e32 v35, v41, v35
	v_cvt_pk_bf16_f32 v36, v32, v33
	v_cvt_pk_bf16_f32 v37, v34, v35
	global_load_dwordx4 v[32:35], v[16:17], off nt
	v_mul_f32_e32 v38, v44, v62
	v_mul_f32_e32 v39, v45, v62
	v_mul_f32_e32 v40, v46, v62
	v_mul_f32_e32 v41, v47, v62
	global_store_dwordx2 v[24:25], v[36:37], off
	s_waitcnt vmcnt(1)
	v_mul_f32_e32 v32, v38, v32
	v_mul_f32_e32 v33, v39, v33
	v_mul_f32_e32 v34, v40, v34
	v_mul_f32_e32 v35, v41, v35
	v_cvt_pk_bf16_f32 v36, v32, v33
	v_cvt_pk_bf16_f32 v37, v34, v35
	global_load_dwordx4 v[32:35], v[18:19], off nt
	v_mul_f32_e32 v38, v48, v62
	v_mul_f32_e32 v39, v49, v62
	v_mul_f32_e32 v40, v50, v62
	v_mul_f32_e32 v41, v51, v62
	global_store_dwordx2 v[24:25], v[36:37], off offset:512
	s_waitcnt vmcnt(1)
	v_mul_f32_e32 v32, v38, v32
	v_mul_f32_e32 v33, v39, v33
	v_mul_f32_e32 v34, v40, v34
	v_mul_f32_e32 v35, v41, v35
	v_cvt_pk_bf16_f32 v36, v32, v33
	v_cvt_pk_bf16_f32 v37, v34, v35
	global_load_dwordx4 v[32:35], v[20:21], off nt
	s_waitcnt vmcnt(0)
	v_mul_f32_e32 v6, v6, v32
	v_mul_f32_e32 v7, v7, v33
	global_store_dwordx2 v[24:25], v[36:37], off offset:1024
	v_mul_f32_e32 v8, v8, v34
	v_mul_f32_e32 v9, v9, v35
	v_cvt_pk_bf16_f32 v6, v6, v7
	v_cvt_pk_bf16_f32 v7, v8, v9
	global_store_dwordx2 v[24:25], v[6:7], off offset:1536
	v_lshl_add_u64 v[24:25], v[24:25], 0, s[10:11]
	s_andn2_b64 exec, exec, s[14:15]
	s_cbranch_execnz .LBB0_56

.LBB0_323:
	s_andn2_b64 vcc, exec, s[42:43]
	s_waitcnt lgkmcnt(0)
	s_barrier
	s_cbranch_vccnz .LBB0_306
	v_div_scale_f32 v3, s[4:5], v0, v0, 1.0
	v_rcp_f32_e32 v4, v3
	s_mov_b64 s[4:5], 0x3000
	v_fma_f32 v5, -v3, v4, 1.0
	v_fmac_f32_e32 v4, v5, v4
	v_div_scale_f32 v5, vcc, 1.0, v0, 1.0
	v_mul_f32_e32 v6, v5, v4
	v_fma_f32 v7, -v3, v6, v5
	v_fmac_f32_e32 v6, v7, v4
	v_fma_f32 v3, -v3, v6, v5
	v_div_fmas_f32 v3, v3, v4, v6
	ds_read2st64_b32 v[232:233], v2 offset0:0 offset1:1
	ds_read2st64_b32 v[234:235], v2 offset0:2 offset1:3
	ds_read2st64_b32 v[236:237], v2 offset0:4 offset1:5
	ds_read2st64_b32 v[238:239], v2 offset0:6 offset1:7
	ds_read2st64_b32 v[240:241], v2 offset0:8 offset1:9
	ds_read2st64_b32 v[242:243], v2 offset0:10 offset1:11
	ds_read2st64_b32 v[244:245], v2 offset0:12 offset1:13
	ds_read2st64_b32 v[246:247], v2 offset0:14 offset1:15
	ds_read2st64_b32 v[208:209], v2 offset0:16 offset1:17
	ds_read2st64_b32 v[210:211], v2 offset0:18 offset1:19
	ds_read2st64_b32 v[212:213], v2 offset0:20 offset1:21
	ds_read2st64_b32 v[214:215], v2 offset0:22 offset1:23
	v_div_fixup_f32 v0, v3, v0, 1.0
	v_add_u32_e32 v10, s35, v195
	v_ashrrev_i32_e32 v11, 31, v10
	v_lshlrev_b64 v[8:9], 14, v[10:11]
	v_lshlrev_b64 v[10:11], 12, v[10:11]
	v_lshl_add_u64 v[8:9], s[52:53], 0, v[8:9]
	v_lshlrev_b32_e32 v6, 4, v205
	v_mov_b32_e32 v7, 0
	v_lshl_add_u64 v[8:9], v[8:9], 0, s[36:37]
	v_lshl_add_u64 v[10:11], s[58:59], 0, v[10:11]
	v_lshl_add_u64 v[8:9], v[8:9], 0, v[6:7]
	v_lshl_add_u64 v[10:11], v[10:11], 0, v[6:7]
	v_lshl_add_u64 v[8:9], v[8:9], 0, s[4:5]
	s_mov_b64 s[4:5], 0x8000
	global_load_dwordx4 v[144:147], v[8:9], off nt
	v_lshl_add_u64 v[8:9], v[8:9], 0, s[4:5]
	global_load_dwordx4 v[148:151], v[8:9], off nt
	v_lshl_add_u64 v[8:9], v[8:9], 0, s[4:5]
	global_load_dwordx4 v[152:155], v[8:9], off nt
	v_lshl_add_u64 v[8:9], v[8:9], 0, s[4:5]
	global_load_dwordx4 v[156:159], v[8:9], off nt
	v_lshl_add_u64 v[8:9], v[8:9], 0, s[4:5]
	global_load_dwordx4 v[160:163], v[8:9], off nt
	v_lshl_add_u64 v[8:9], v[8:9], 0, s[4:5]
	global_load_dwordx4 v[164:167], v[8:9], off nt
	v_lshl_add_u64 v[8:9], v[8:9], 0, s[4:5]
	global_load_dwordx4 v[168:171], v[8:9], off nt
	v_lshl_add_u64 v[8:9], v[8:9], 0, s[4:5]
	global_load_dwordx4 v[172:175], v[8:9], off nt
	v_lshl_add_u64 v[8:9], v[8:9], 0, s[4:5]
	global_load_dwordx4 v[176:179], v[8:9], off nt
	v_lshl_add_u64 v[8:9], v[8:9], 0, s[4:5]
	global_load_dwordx4 v[180:183], v[8:9], off nt
	v_lshl_add_u64 v[8:9], v[8:9], 0, s[4:5]
	global_load_dwordx4 v[184:187], v[8:9], off nt
	v_lshl_add_u64 v[8:9], v[8:9], 0, s[4:5]
	global_load_dwordx4 v[188:191], v[8:9], off nt
	v_lshl_add_u64 v[8:9], v[8:9], 0, s[4:5]
	global_load_dwordx4 v[216:219], v[8:9], off nt
	v_lshl_add_u64 v[8:9], v[8:9], 0, s[4:5]
	global_load_dwordx4 v[220:223], v[8:9], off nt
	v_lshl_add_u64 v[8:9], v[8:9], 0, s[4:5]
	global_load_dwordx4 v[224:227], v[8:9], off nt
	v_lshl_add_u64 v[8:9], v[8:9], 0, s[4:5]
	global_load_dwordx4 v[228:231], v[8:9], off nt
	v_mov_b32_e32 v12, 0
	v_mov_b32_e32 v13, 0
	v_mov_b32_e32 v14, 0
	v_mov_b32_e32 v15, 0
	s_waitcnt lgkmcnt(8)
	v_fma_f32 v128, v128, v0, -v232
	v_fma_f32 v129, v129, v0, -v233
	v_fma_f32 v130, v130, v0, -v234
	v_fma_f32 v131, v131, v0, -v235
	v_fma_f32 v132, v132, v0, -v236
	v_fma_f32 v133, v133, v0, -v237
	v_fma_f32 v134, v134, v0, -v238
	v_fma_f32 v135, v135, v0, -v239
	v_fmac_f32_e32 v12, v128, v128
	v_fmac_f32_e32 v13, v129, v129
	v_fmac_f32_e32 v14, v130, v130
	v_fmac_f32_e32 v15, v131, v131
	v_fmac_f32_e32 v12, v132, v132
	v_fmac_f32_e32 v13, v133, v133
	v_fmac_f32_e32 v14, v134, v134
	v_fmac_f32_e32 v15, v135, v135
	ds_read2st64_b32 v[232:233], v2 offset0:24 offset1:25
	ds_read2st64_b32 v[234:235], v2 offset0:26 offset1:27
	ds_read2st64_b32 v[236:237], v2 offset0:28 offset1:29
	ds_read2st64_b32 v[238:239], v2 offset0:30 offset1:31
	s_waitcnt lgkmcnt(8)
	v_fma_f32 v136, v136, v0, -v240
	v_fma_f32 v137, v137, v0, -v241
	v_fma_f32 v138, v138, v0, -v242
	v_fma_f32 v139, v139, v0, -v243
	v_fma_f32 v140, v140, v0, -v244
	v_fma_f32 v141, v141, v0, -v245
	v_fma_f32 v142, v142, v0, -v246
	v_fma_f32 v143, v143, v0, -v247
	v_fmac_f32_e32 v12, v136, v136
	v_fmac_f32_e32 v13, v137, v137
	v_fmac_f32_e32 v14, v138, v138
	v_fmac_f32_e32 v15, v139, v139
	v_fmac_f32_e32 v12, v140, v140
	v_fmac_f32_e32 v13, v141, v141
	v_fmac_f32_e32 v14, v142, v142
	v_fmac_f32_e32 v15, v143, v143
	ds_read2st64_b32 v[240:241], v2 offset0:32 offset1:33
	ds_read2st64_b32 v[242:243], v2 offset0:34 offset1:35
	ds_read2st64_b32 v[244:245], v2 offset0:36 offset1:37
	ds_read2st64_b32 v[246:247], v2 offset0:38 offset1:39
	s_waitcnt lgkmcnt(8)
	v_fma_f32 v112, v112, v0, -v208
	v_fma_f32 v113, v113, v0, -v209
	v_fma_f32 v114, v114, v0, -v210
	v_fma_f32 v115, v115, v0, -v211
	v_fma_f32 v116, v116, v0, -v212
	v_fma_f32 v117, v117, v0, -v213
	v_fma_f32 v118, v118, v0, -v214
	v_fma_f32 v119, v119, v0, -v215
	v_fmac_f32_e32 v12, v112, v112
	v_fmac_f32_e32 v13, v113, v113
	v_fmac_f32_e32 v14, v114, v114
	v_fmac_f32_e32 v15, v115, v115
	v_fmac_f32_e32 v12, v116, v116
	v_fmac_f32_e32 v13, v117, v117
	v_fmac_f32_e32 v14, v118, v118
	v_fmac_f32_e32 v15, v119, v119
	ds_read2st64_b32 v[208:209], v2 offset0:40 offset1:41
	ds_read2st64_b32 v[210:211], v2 offset0:42 offset1:43
	ds_read2st64_b32 v[212:213], v2 offset0:44 offset1:45
	ds_read2st64_b32 v[214:215], v2 offset0:46 offset1:47
	s_waitcnt lgkmcnt(8)
	v_fma_f32 v120, v120, v0, -v232
	v_fma_f32 v121, v121, v0, -v233
	v_fma_f32 v122, v122, v0, -v234
	v_fma_f32 v123, v123, v0, -v235
	v_fma_f32 v124, v124, v0, -v236
	v_fma_f32 v125, v125, v0, -v237
	v_fma_f32 v126, v126, v0, -v238
	v_fma_f32 v127, v127, v0, -v239
	v_fmac_f32_e32 v12, v120, v120
	v_fmac_f32_e32 v13, v121, v121
	v_fmac_f32_e32 v14, v122, v122
	v_fmac_f32_e32 v15, v123, v123
	v_fmac_f32_e32 v12, v124, v124
	v_fmac_f32_e32 v13, v125, v125
	v_fmac_f32_e32 v14, v126, v126
	v_fmac_f32_e32 v15, v127, v127
	ds_read2st64_b32 v[232:233], v2 offset0:48 offset1:49
	ds_read2st64_b32 v[234:235], v2 offset0:50 offset1:51
	ds_read2st64_b32 v[236:237], v2 offset0:52 offset1:53
	ds_read2st64_b32 v[238:239], v2 offset0:54 offset1:55
	s_waitcnt lgkmcnt(8)
	v_fma_f32 v96, v96, v0, -v240
	v_fma_f32 v97, v97, v0, -v241
	v_fma_f32 v98, v98, v0, -v242
	v_fma_f32 v99, v99, v0, -v243
	v_fma_f32 v100, v100, v0, -v244
	v_fma_f32 v101, v101, v0, -v245
	v_fma_f32 v102, v102, v0, -v246
	v_fma_f32 v103, v103, v0, -v247
	v_fmac_f32_e32 v12, v96, v96
	v_fmac_f32_e32 v13, v97, v97
	v_fmac_f32_e32 v14, v98, v98
	v_fmac_f32_e32 v15, v99, v99
	v_fmac_f32_e32 v12, v100, v100
	v_fmac_f32_e32 v13, v101, v101
	v_fmac_f32_e32 v14, v102, v102
	v_fmac_f32_e32 v15, v103, v103
	ds_read2st64_b32 v[240:241], v2 offset0:56 offset1:57
	ds_read2st64_b32 v[242:243], v2 offset0:58 offset1:59
	ds_read2st64_b32 v[244:245], v2 offset0:60 offset1:61
	ds_read2st64_b32 v[246:247], v2 offset0:62 offset1:63
	s_waitcnt lgkmcnt(8)
	v_fma_f32 v104, v104, v0, -v208
	v_fma_f32 v105, v105, v0, -v209
	v_fma_f32 v106, v106, v0, -v210
	v_fma_f32 v107, v107, v0, -v211
	v_fma_f32 v108, v108, v0, -v212
	v_fma_f32 v109, v109, v0, -v213
	v_fma_f32 v110, v110, v0, -v214
	v_fma_f32 v111, v111, v0, -v215
	v_fmac_f32_e32 v12, v104, v104
	v_fmac_f32_e32 v13, v105, v105
	v_fmac_f32_e32 v14, v106, v106
	v_fmac_f32_e32 v15, v107, v107
	v_fmac_f32_e32 v12, v108, v108
	v_fmac_f32_e32 v13, v109, v109
	v_fmac_f32_e32 v14, v110, v110
	v_fmac_f32_e32 v15, v111, v111
	ds_read2st64_b32 v[208:209], v2 offset0:64 offset1:65
	ds_read2st64_b32 v[210:211], v2 offset0:66 offset1:67
	ds_read2st64_b32 v[212:213], v2 offset0:68 offset1:69
	ds_read2st64_b32 v[214:215], v2 offset0:70 offset1:71
	s_waitcnt lgkmcnt(8)
	v_fma_f32 v80, v80, v0, -v232
	v_fma_f32 v81, v81, v0, -v233
	v_fma_f32 v82, v82, v0, -v234
	v_fma_f32 v83, v83, v0, -v235
	v_fma_f32 v84, v84, v0, -v236
	v_fma_f32 v85, v85, v0, -v237
	v_fma_f32 v86, v86, v0, -v238
	v_fma_f32 v87, v87, v0, -v239
	v_fmac_f32_e32 v12, v80, v80
	v_fmac_f32_e32 v13, v81, v81
	v_fmac_f32_e32 v14, v82, v82
	v_fmac_f32_e32 v15, v83, v83
	v_fmac_f32_e32 v12, v84, v84
	v_fmac_f32_e32 v13, v85, v85
	v_fmac_f32_e32 v14, v86, v86
	v_fmac_f32_e32 v15, v87, v87
	ds_read2st64_b32 v[232:233], v2 offset0:72 offset1:73
	ds_read2st64_b32 v[234:235], v2 offset0:74 offset1:75
	ds_read2st64_b32 v[236:237], v2 offset0:76 offset1:77
	ds_read2st64_b32 v[238:239], v2 offset0:78 offset1:79
	s_waitcnt lgkmcnt(8)
	v_fma_f32 v88, v88, v0, -v240
	v_fma_f32 v89, v89, v0, -v241
	v_fma_f32 v90, v90, v0, -v242
	v_fma_f32 v91, v91, v0, -v243
	v_fma_f32 v92, v92, v0, -v244
	v_fma_f32 v93, v93, v0, -v245
	v_fma_f32 v94, v94, v0, -v246
	v_fma_f32 v95, v95, v0, -v247
	v_fmac_f32_e32 v12, v88, v88
	v_fmac_f32_e32 v13, v89, v89
	v_fmac_f32_e32 v14, v90, v90
	v_fmac_f32_e32 v15, v91, v91
	v_fmac_f32_e32 v12, v92, v92
	v_fmac_f32_e32 v13, v93, v93
	v_fmac_f32_e32 v14, v94, v94
	v_fmac_f32_e32 v15, v95, v95
	ds_read2st64_b32 v[240:241], v2 offset0:80 offset1:81
	ds_read2st64_b32 v[242:243], v2 offset0:82 offset1:83
	ds_read2st64_b32 v[244:245], v2 offset0:84 offset1:85
	ds_read2st64_b32 v[246:247], v2 offset0:86 offset1:87
	s_waitcnt lgkmcnt(8)
	v_fma_f32 v64, v64, v0, -v208
	v_fma_f32 v65, v65, v0, -v209
	v_fma_f32 v66, v66, v0, -v210
	v_fma_f32 v67, v67, v0, -v211
	v_fma_f32 v68, v68, v0, -v212
	v_fma_f32 v69, v69, v0, -v213
	v_fma_f32 v70, v70, v0, -v214
	v_fma_f32 v71, v71, v0, -v215
	v_fmac_f32_e32 v12, v64, v64
	v_fmac_f32_e32 v13, v65, v65
	v_fmac_f32_e32 v14, v66, v66
	v_fmac_f32_e32 v15, v67, v67
	v_fmac_f32_e32 v12, v68, v68
	v_fmac_f32_e32 v13, v69, v69
	v_fmac_f32_e32 v14, v70, v70
	v_fmac_f32_e32 v15, v71, v71
	ds_read2st64_b32 v[208:209], v2 offset0:88 offset1:89
	ds_read2st64_b32 v[210:211], v2 offset0:90 offset1:91
	ds_read2st64_b32 v[212:213], v2 offset0:92 offset1:93
	ds_read2st64_b32 v[214:215], v2 offset0:94 offset1:95
	s_waitcnt lgkmcnt(8)
	v_fma_f32 v72, v72, v0, -v232
	v_fma_f32 v73, v73, v0, -v233
	v_fma_f32 v74, v74, v0, -v234
	v_fma_f32 v75, v75, v0, -v235
	v_fma_f32 v76, v76, v0, -v236
	v_fma_f32 v77, v77, v0, -v237
	v_fma_f32 v78, v78, v0, -v238
	v_fma_f32 v79, v79, v0, -v239
	v_fmac_f32_e32 v12, v72, v72
	v_fmac_f32_e32 v13, v73, v73
	v_fmac_f32_e32 v14, v74, v74
	v_fmac_f32_e32 v15, v75, v75
	v_fmac_f32_e32 v12, v76, v76
	v_fmac_f32_e32 v13, v77, v77
	v_fmac_f32_e32 v14, v78, v78
	v_fmac_f32_e32 v15, v79, v79
	ds_read2st64_b32 v[232:233], v2 offset0:96 offset1:97
	ds_read2st64_b32 v[234:235], v2 offset0:98 offset1:99
	ds_read2st64_b32 v[236:237], v2 offset0:100 offset1:101
	ds_read2st64_b32 v[238:239], v2 offset0:102 offset1:103
	s_waitcnt lgkmcnt(8)
	v_fma_f32 v48, v48, v0, -v240
	v_fma_f32 v49, v49, v0, -v241
	v_fma_f32 v50, v50, v0, -v242
	v_fma_f32 v51, v51, v0, -v243
	v_fma_f32 v52, v52, v0, -v244
	v_fma_f32 v53, v53, v0, -v245
	v_fma_f32 v54, v54, v0, -v246
	v_fma_f32 v55, v55, v0, -v247
	v_fmac_f32_e32 v12, v48, v48
	v_fmac_f32_e32 v13, v49, v49
	v_fmac_f32_e32 v14, v50, v50
	v_fmac_f32_e32 v15, v51, v51
	v_fmac_f32_e32 v12, v52, v52
	v_fmac_f32_e32 v13, v53, v53
	v_fmac_f32_e32 v14, v54, v54
	v_fmac_f32_e32 v15, v55, v55
	ds_read2st64_b32 v[240:241], v2 offset0:104 offset1:105
	ds_read2st64_b32 v[242:243], v2 offset0:106 offset1:107
	ds_read2st64_b32 v[244:245], v2 offset0:108 offset1:109
	ds_read2st64_b32 v[246:247], v2 offset0:110 offset1:111
	s_waitcnt lgkmcnt(8)
	v_fma_f32 v56, v56, v0, -v208
	v_fma_f32 v57, v57, v0, -v209
	v_fma_f32 v58, v58, v0, -v210
	v_fma_f32 v59, v59, v0, -v211
	v_fma_f32 v60, v60, v0, -v212
	v_fma_f32 v61, v61, v0, -v213
	v_fma_f32 v62, v62, v0, -v214
	v_fma_f32 v63, v63, v0, -v215
	v_fmac_f32_e32 v12, v56, v56
	v_fmac_f32_e32 v13, v57, v57
	v_fmac_f32_e32 v14, v58, v58
	v_fmac_f32_e32 v15, v59, v59
	v_fmac_f32_e32 v12, v60, v60
	v_fmac_f32_e32 v13, v61, v61
	v_fmac_f32_e32 v14, v62, v62
	v_fmac_f32_e32 v15, v63, v63
	ds_read2st64_b32 v[208:209], v2 offset0:112 offset1:113
	ds_read2st64_b32 v[210:211], v2 offset0:114 offset1:115
	ds_read2st64_b32 v[212:213], v2 offset0:116 offset1:117
	ds_read2st64_b32 v[214:215], v2 offset0:118 offset1:119
	s_waitcnt lgkmcnt(8)
	v_fma_f32 v32, v32, v0, -v232
	v_fma_f32 v33, v33, v0, -v233
	v_fma_f32 v34, v34, v0, -v234
	v_fma_f32 v35, v35, v0, -v235
	v_fma_f32 v36, v36, v0, -v236
	v_fma_f32 v37, v37, v0, -v237
	v_fma_f32 v38, v38, v0, -v238
	v_fma_f32 v39, v39, v0, -v239
	v_fmac_f32_e32 v12, v32, v32
	v_fmac_f32_e32 v13, v33, v33
	v_fmac_f32_e32 v14, v34, v34
	v_fmac_f32_e32 v15, v35, v35
	v_fmac_f32_e32 v12, v36, v36
	v_fmac_f32_e32 v13, v37, v37
	v_fmac_f32_e32 v14, v38, v38
	v_fmac_f32_e32 v15, v39, v39
	ds_read2st64_b32 v[232:233], v2 offset0:120 offset1:121
	ds_read2st64_b32 v[234:235], v2 offset0:122 offset1:123
	ds_read2st64_b32 v[236:237], v2 offset0:124 offset1:125
	ds_read2st64_b32 v[238:239], v2 offset0:126 offset1:127
	s_waitcnt lgkmcnt(8)
	v_fma_f32 v40, v40, v0, -v240
	v_fma_f32 v41, v41, v0, -v241
	v_fma_f32 v42, v42, v0, -v242
	v_fma_f32 v43, v43, v0, -v243
	v_fma_f32 v44, v44, v0, -v244
	v_fma_f32 v45, v45, v0, -v245
	v_fma_f32 v46, v46, v0, -v246
	v_fma_f32 v47, v47, v0, -v247
	v_fmac_f32_e32 v12, v40, v40
	v_fmac_f32_e32 v13, v41, v41
	v_fmac_f32_e32 v14, v42, v42
	v_fmac_f32_e32 v15, v43, v43
	v_fmac_f32_e32 v12, v44, v44
	v_fmac_f32_e32 v13, v45, v45
	v_fmac_f32_e32 v14, v46, v46
	v_fmac_f32_e32 v15, v47, v47
	s_waitcnt lgkmcnt(4)
	v_fma_f32 v16, v16, v0, -v208
	v_fma_f32 v17, v17, v0, -v209
	v_fma_f32 v18, v18, v0, -v210
	v_fma_f32 v19, v19, v0, -v211
	v_fma_f32 v20, v20, v0, -v212
	v_fma_f32 v21, v21, v0, -v213
	v_fma_f32 v22, v22, v0, -v214
	v_fma_f32 v23, v23, v0, -v215
	v_fmac_f32_e32 v12, v16, v16
	v_fmac_f32_e32 v13, v17, v17
	v_fmac_f32_e32 v14, v18, v18
	v_fmac_f32_e32 v15, v19, v19
	v_fmac_f32_e32 v12, v20, v20
	v_fmac_f32_e32 v13, v21, v21
	v_fmac_f32_e32 v14, v22, v22
	v_fmac_f32_e32 v15, v23, v23
	s_waitcnt lgkmcnt(0)
	v_fma_f32 v24, v24, v0, -v232
	v_fma_f32 v25, v25, v0, -v233
	v_fma_f32 v26, v26, v0, -v234
	v_fma_f32 v27, v27, v0, -v235
	v_fma_f32 v28, v28, v0, -v236
	v_fma_f32 v29, v29, v0, -v237
	v_fma_f32 v30, v30, v0, -v238
	v_fma_f32 v31, v31, v0, -v239
	v_fmac_f32_e32 v12, v24, v24
	v_fmac_f32_e32 v13, v25, v25
	v_fmac_f32_e32 v14, v26, v26
	v_fmac_f32_e32 v15, v27, v27
	v_fmac_f32_e32 v12, v28, v28
	v_fmac_f32_e32 v13, v29, v29
	v_fmac_f32_e32 v14, v30, v30
	v_fmac_f32_e32 v15, v31, v31
	v_lshlrev_b32_e32 v2, 4, v195
	v_add_u32_e32 v2, 0x23800, v2
	ds_read_b128 v[232:235], v2 offset:0
	ds_read_b128 v[236:239], v2 offset:32
	ds_read_b128 v[240:243], v2 offset:64
	ds_read_b128 v[244:247], v2 offset:96
	ds_read_b128 v[208:211], v2 offset:128
	ds_read_b128 v[212:215], v2 offset:160
	v_add_f32_e32 v12, v12, v13
	v_add_f32_e32 v14, v14, v15
	v_add_f32_e32 v12, v12, v14
	v_mov_b32_e32 v13, v12
	s_nop 1
	v_permlane32_swap_b32_e32 v12, v13
	v_add_f32_e32 v12, v12, v13
	v_mov_b32_e32 v13, 0x3727c5ac
	v_fmamk_f32 v12, v12, 0x3b800000, v13
	v_cmp_gt_f32_e32 vcc, s81, v12
	v_mul_f32_e32 v13, 0x4b800000, v12
	s_nop 0
	v_cndmask_b32_e32 v12, v12, v13, vcc
	v_rsq_f32_e32 v12, v12
	s_nop 0
	v_mul_f32_e32 v13, 0x45800000, v12
	v_cndmask_b32_e32 v12, v12, v13, vcc
	v_mul_f32_e32 v0, v194, v12
	v_and_b32_e32 v3, 7, v205
	v_xor_b32_e32 v3, v3, v195
	v_lshlrev_b32_e32 v3, 4, v3
	v_lshl_add_u32 v3, v205, 10, v3
	v_add_u32_e32 v3, s76, v3
	v_lshlrev_b32_e32 v9, 5, v205
	v_lshlrev_b32_e32 v8, 4, v195
	v_xor_b32_e32 v9, v9, v8
	v_lshl_add_u32 v9, v195, 10, v9
	v_add_u32_e32 v9, s76, v9
	s_waitcnt lgkmcnt(4)
	v_mul_f32_e32 v4, v128, v0
	v_mul_f32_e32 v5, v129, v0
	v_mul_f32_e32 v6, v130, v0
	v_mul_f32_e32 v7, v131, v0
	v_mul_f32_e32 v4, v232, v4
	v_mul_f32_e32 v5, v233, v5
	v_mul_f32_e32 v6, v234, v6
	v_mul_f32_e32 v7, v235, v7
	ds_write_b128 v3, v[4:7]
	v_mul_f32_e32 v12, v132, v0
	v_mul_f32_e32 v13, v133, v0
	v_mul_f32_e32 v14, v134, v0
	v_mul_f32_e32 v15, v135, v0
	v_mul_f32_e32 v12, v236, v12
	v_mul_f32_e32 v13, v237, v13
	v_mul_f32_e32 v14, v238, v14
	v_mul_f32_e32 v15, v239, v15
	v_xor_b32_e32 v8, 0x20, v3
	ds_write_b128 v8, v[12:15]
	ds_read_b128 v[232:235], v2 offset:192
	ds_read_b128 v[236:239], v2 offset:224
	s_waitcnt lgkmcnt(6)
	v_mul_f32_e32 v4, v136, v0
	v_mul_f32_e32 v5, v137, v0
	v_mul_f32_e32 v6, v138, v0
	v_mul_f32_e32 v7, v139, v0
	v_mul_f32_e32 v4, v240, v4
	v_mul_f32_e32 v5, v241, v5
	v_mul_f32_e32 v6, v242, v6
	v_mul_f32_e32 v7, v243, v7
	v_xor_b32_e32 v8, 0x40, v3
	ds_write_b128 v8, v[4:7]
	v_mul_f32_e32 v12, v140, v0
	v_mul_f32_e32 v13, v141, v0
	v_mul_f32_e32 v14, v142, v0
	v_mul_f32_e32 v15, v143, v0
	v_mul_f32_e32 v12, v244, v12
	v_mul_f32_e32 v13, v245, v13
	v_mul_f32_e32 v14, v246, v14
	v_mul_f32_e32 v15, v247, v15
	v_xor_b32_e32 v8, 0x60, v3
	ds_write_b128 v8, v[12:15]
	ds_read_b128 v[240:243], v2 offset:256
	ds_read_b128 v[244:247], v2 offset:288
	s_waitcnt lgkmcnt(8)
	v_mul_f32_e32 v4, v112, v0
	v_mul_f32_e32 v5, v113, v0
	v_mul_f32_e32 v6, v114, v0
	v_mul_f32_e32 v7, v115, v0
	v_mul_f32_e32 v4, v208, v4
	v_mul_f32_e32 v5, v209, v5
	v_mul_f32_e32 v6, v210, v6
	v_mul_f32_e32 v7, v211, v7
	v_xor_b32_e32 v8, 0x80, v3
	ds_write_b128 v8, v[4:7]
	v_mul_f32_e32 v12, v116, v0
	v_mul_f32_e32 v13, v117, v0
	v_mul_f32_e32 v14, v118, v0
	v_mul_f32_e32 v15, v119, v0
	v_mul_f32_e32 v12, v212, v12
	v_mul_f32_e32 v13, v213, v13
	v_mul_f32_e32 v14, v214, v14
	v_mul_f32_e32 v15, v215, v15
	v_xor_b32_e32 v8, 0xa0, v3
	ds_write_b128 v8, v[12:15]
	ds_read_b128 v[208:211], v2 offset:320
	ds_read_b128 v[212:215], v2 offset:352
	s_waitcnt lgkmcnt(8)
	v_mul_f32_e32 v4, v120, v0
	v_mul_f32_e32 v5, v121, v0
	v_mul_f32_e32 v6, v122, v0
	v_mul_f32_e32 v7, v123, v0
	v_mul_f32_e32 v4, v232, v4
	v_mul_f32_e32 v5, v233, v5
	v_mul_f32_e32 v6, v234, v6
	v_mul_f32_e32 v7, v235, v7
	v_xor_b32_e32 v8, 0xc0, v3
	ds_write_b128 v8, v[4:7]
	v_mul_f32_e32 v12, v124, v0
	v_mul_f32_e32 v13, v125, v0
	v_mul_f32_e32 v14, v126, v0
	v_mul_f32_e32 v15, v127, v0
	v_mul_f32_e32 v12, v236, v12
	v_mul_f32_e32 v13, v237, v13
	v_mul_f32_e32 v14, v238, v14
	v_mul_f32_e32 v15, v239, v15
	v_xor_b32_e32 v8, 0xe0, v3
	ds_write_b128 v8, v[12:15]
	ds_read_b128 v[232:235], v2 offset:384
	ds_read_b128 v[236:239], v2 offset:416
	s_waitcnt lgkmcnt(8)
	v_mul_f32_e32 v4, v96, v0
	v_mul_f32_e32 v5, v97, v0
	v_mul_f32_e32 v6, v98, v0
	v_mul_f32_e32 v7, v99, v0
	v_mul_f32_e32 v4, v240, v4
	v_mul_f32_e32 v5, v241, v5
	v_mul_f32_e32 v6, v242, v6
	v_mul_f32_e32 v7, v243, v7
	v_xor_b32_e32 v8, 0x100, v3
	ds_write_b128 v8, v[4:7]
	v_mul_f32_e32 v12, v100, v0
	v_mul_f32_e32 v13, v101, v0
	v_mul_f32_e32 v14, v102, v0
	v_mul_f32_e32 v15, v103, v0
	v_mul_f32_e32 v12, v244, v12
	v_mul_f32_e32 v13, v245, v13
	v_mul_f32_e32 v14, v246, v14
	v_mul_f32_e32 v15, v247, v15
	v_xor_b32_e32 v8, 0x120, v3
	ds_write_b128 v8, v[12:15]
	ds_read_b128 v[240:243], v2 offset:448
	ds_read_b128 v[244:247], v2 offset:480
	s_waitcnt lgkmcnt(8)
	v_mul_f32_e32 v4, v104, v0
	v_mul_f32_e32 v5, v105, v0
	v_mul_f32_e32 v6, v106, v0
	v_mul_f32_e32 v7, v107, v0
	v_mul_f32_e32 v4, v208, v4
	v_mul_f32_e32 v5, v209, v5
	v_mul_f32_e32 v6, v210, v6
	v_mul_f32_e32 v7, v211, v7
	v_xor_b32_e32 v8, 0x140, v3
	ds_write_b128 v8, v[4:7]
	v_mul_f32_e32 v12, v108, v0
	v_mul_f32_e32 v13, v109, v0
	v_mul_f32_e32 v14, v110, v0
	v_mul_f32_e32 v15, v111, v0
	v_mul_f32_e32 v12, v212, v12
	v_mul_f32_e32 v13, v213, v13
	v_mul_f32_e32 v14, v214, v14
	v_mul_f32_e32 v15, v215, v15
	v_xor_b32_e32 v8, 0x160, v3
	ds_write_b128 v8, v[12:15]
	ds_read_b128 v[208:211], v2 offset:512
	ds_read_b128 v[212:215], v2 offset:544
	s_waitcnt lgkmcnt(8)
	v_mul_f32_e32 v4, v80, v0
	v_mul_f32_e32 v5, v81, v0
	v_mul_f32_e32 v6, v82, v0
	v_mul_f32_e32 v7, v83, v0
	v_mul_f32_e32 v4, v232, v4
	v_mul_f32_e32 v5, v233, v5
	v_mul_f32_e32 v6, v234, v6
	v_mul_f32_e32 v7, v235, v7
	v_xor_b32_e32 v8, 0x180, v3
	ds_write_b128 v8, v[4:7]
	v_mul_f32_e32 v12, v84, v0
	v_mul_f32_e32 v13, v85, v0
	v_mul_f32_e32 v14, v86, v0
	v_mul_f32_e32 v15, v87, v0
	v_mul_f32_e32 v12, v236, v12
	v_mul_f32_e32 v13, v237, v13
	v_mul_f32_e32 v14, v238, v14
	v_mul_f32_e32 v15, v239, v15
	v_xor_b32_e32 v8, 0x1a0, v3
	ds_write_b128 v8, v[12:15]
	ds_read_b128 v[232:235], v2 offset:576
	ds_read_b128 v[236:239], v2 offset:608
	s_waitcnt lgkmcnt(8)
	v_mul_f32_e32 v4, v88, v0
	v_mul_f32_e32 v5, v89, v0
	v_mul_f32_e32 v6, v90, v0
	v_mul_f32_e32 v7, v91, v0
	v_mul_f32_e32 v4, v240, v4
	v_mul_f32_e32 v5, v241, v5
	v_mul_f32_e32 v6, v242, v6
	v_mul_f32_e32 v7, v243, v7
	v_xor_b32_e32 v8, 0x1c0, v3
	ds_write_b128 v8, v[4:7]
	v_mul_f32_e32 v12, v92, v0
	v_mul_f32_e32 v13, v93, v0
	v_mul_f32_e32 v14, v94, v0
	v_mul_f32_e32 v15, v95, v0
	v_mul_f32_e32 v12, v244, v12
	v_mul_f32_e32 v13, v245, v13
	v_mul_f32_e32 v14, v246, v14
	v_mul_f32_e32 v15, v247, v15
	v_xor_b32_e32 v8, 0x1e0, v3
	ds_write_b128 v8, v[12:15]
	ds_read_b128 v[240:243], v2 offset:640
	ds_read_b128 v[244:247], v2 offset:672
	s_waitcnt lgkmcnt(8)
	v_mul_f32_e32 v4, v64, v0
	v_mul_f32_e32 v5, v65, v0
	v_mul_f32_e32 v6, v66, v0
	v_mul_f32_e32 v7, v67, v0
	v_mul_f32_e32 v4, v208, v4
	v_mul_f32_e32 v5, v209, v5
	v_mul_f32_e32 v6, v210, v6
	v_mul_f32_e32 v7, v211, v7
	v_xor_b32_e32 v8, 0x200, v3
	ds_write_b128 v8, v[4:7]
	v_mul_f32_e32 v12, v68, v0
	v_mul_f32_e32 v13, v69, v0
	v_mul_f32_e32 v14, v70, v0
	v_mul_f32_e32 v15, v71, v0
	v_mul_f32_e32 v12, v212, v12
	v_mul_f32_e32 v13, v213, v13
	v_mul_f32_e32 v14, v214, v14
	v_mul_f32_e32 v15, v215, v15
	v_xor_b32_e32 v8, 0x220, v3
	ds_write_b128 v8, v[12:15]
	ds_read_b128 v[208:211], v2 offset:704
	ds_read_b128 v[212:215], v2 offset:736
	s_waitcnt lgkmcnt(8)
	v_mul_f32_e32 v4, v72, v0
	v_mul_f32_e32 v5, v73, v0
	v_mul_f32_e32 v6, v74, v0
	v_mul_f32_e32 v7, v75, v0
	v_mul_f32_e32 v4, v232, v4
	v_mul_f32_e32 v5, v233, v5
	v_mul_f32_e32 v6, v234, v6
	v_mul_f32_e32 v7, v235, v7
	v_xor_b32_e32 v8, 0x240, v3
	ds_write_b128 v8, v[4:7]
	v_mul_f32_e32 v12, v76, v0
	v_mul_f32_e32 v13, v77, v0
	v_mul_f32_e32 v14, v78, v0
	v_mul_f32_e32 v15, v79, v0
	v_mul_f32_e32 v12, v236, v12
	v_mul_f32_e32 v13, v237, v13
	v_mul_f32_e32 v14, v238, v14
	v_mul_f32_e32 v15, v239, v15
	v_xor_b32_e32 v8, 0x260, v3
	ds_write_b128 v8, v[12:15]
	ds_read_b128 v[232:235], v2 offset:768
	ds_read_b128 v[236:239], v2 offset:800
	s_waitcnt lgkmcnt(8)
	v_mul_f32_e32 v4, v48, v0
	v_mul_f32_e32 v5, v49, v0
	v_mul_f32_e32 v6, v50, v0
	v_mul_f32_e32 v7, v51, v0
	v_mul_f32_e32 v4, v240, v4
	v_mul_f32_e32 v5, v241, v5
	v_mul_f32_e32 v6, v242, v6
	v_mul_f32_e32 v7, v243, v7
	v_xor_b32_e32 v8, 0x280, v3
	ds_write_b128 v8, v[4:7]
	v_mul_f32_e32 v12, v52, v0
	v_mul_f32_e32 v13, v53, v0
	v_mul_f32_e32 v14, v54, v0
	v_mul_f32_e32 v15, v55, v0
	v_mul_f32_e32 v12, v244, v12
	v_mul_f32_e32 v13, v245, v13
	v_mul_f32_e32 v14, v246, v14
	v_mul_f32_e32 v15, v247, v15
	v_xor_b32_e32 v8, 0x2a0, v3
	ds_write_b128 v8, v[12:15]
	ds_read_b128 v[240:243], v2 offset:832
	ds_read_b128 v[244:247], v2 offset:864
	s_waitcnt lgkmcnt(8)
	v_mul_f32_e32 v4, v56, v0
	v_mul_f32_e32 v5, v57, v0
	v_mul_f32_e32 v6, v58, v0
	v_mul_f32_e32 v7, v59, v0
	v_mul_f32_e32 v4, v208, v4
	v_mul_f32_e32 v5, v209, v5
	v_mul_f32_e32 v6, v210, v6
	v_mul_f32_e32 v7, v211, v7
	v_xor_b32_e32 v8, 0x2c0, v3
	ds_write_b128 v8, v[4:7]
	v_mul_f32_e32 v12, v60, v0
	v_mul_f32_e32 v13, v61, v0
	v_mul_f32_e32 v14, v62, v0
	v_mul_f32_e32 v15, v63, v0
	v_mul_f32_e32 v12, v212, v12
	v_mul_f32_e32 v13, v213, v13
	v_mul_f32_e32 v14, v214, v14
	v_mul_f32_e32 v15, v215, v15
	v_xor_b32_e32 v8, 0x2e0, v3
	ds_write_b128 v8, v[12:15]
	ds_read_b128 v[208:211], v2 offset:896
	ds_read_b128 v[212:215], v2 offset:928
	s_waitcnt lgkmcnt(8)
	v_mul_f32_e32 v4, v32, v0
	v_mul_f32_e32 v5, v33, v0
	v_mul_f32_e32 v6, v34, v0
	v_mul_f32_e32 v7, v35, v0
	v_mul_f32_e32 v4, v232, v4
	v_mul_f32_e32 v5, v233, v5
	v_mul_f32_e32 v6, v234, v6
	v_mul_f32_e32 v7, v235, v7
	v_xor_b32_e32 v8, 0x300, v3
	ds_write_b128 v8, v[4:7]
	v_mul_f32_e32 v12, v36, v0
	v_mul_f32_e32 v13, v37, v0
	v_mul_f32_e32 v14, v38, v0
	v_mul_f32_e32 v15, v39, v0
	v_mul_f32_e32 v12, v236, v12
	v_mul_f32_e32 v13, v237, v13
	v_mul_f32_e32 v14, v238, v14
	v_mul_f32_e32 v15, v239, v15
	v_xor_b32_e32 v8, 0x320, v3
	ds_write_b128 v8, v[12:15]
	ds_read_b128 v[232:235], v2 offset:960
	ds_read_b128 v[236:239], v2 offset:992
	s_waitcnt lgkmcnt(8)
	v_mul_f32_e32 v4, v40, v0
	v_mul_f32_e32 v5, v41, v0
	v_mul_f32_e32 v6, v42, v0
	v_mul_f32_e32 v7, v43, v0
	v_mul_f32_e32 v4, v240, v4
	v_mul_f32_e32 v5, v241, v5
	v_mul_f32_e32 v6, v242, v6
	v_mul_f32_e32 v7, v243, v7
	v_xor_b32_e32 v8, 0x340, v3
	ds_write_b128 v8, v[4:7]
	v_mul_f32_e32 v12, v44, v0
	v_mul_f32_e32 v13, v45, v0
	v_mul_f32_e32 v14, v46, v0
	v_mul_f32_e32 v15, v47, v0
	v_mul_f32_e32 v12, v244, v12
	v_mul_f32_e32 v13, v245, v13
	v_mul_f32_e32 v14, v246, v14
	v_mul_f32_e32 v15, v247, v15
	v_xor_b32_e32 v8, 0x360, v3
	ds_write_b128 v8, v[12:15]
	s_waitcnt lgkmcnt(6)
	v_mul_f32_e32 v4, v16, v0
	v_mul_f32_e32 v5, v17, v0
	v_mul_f32_e32 v6, v18, v0
	v_mul_f32_e32 v7, v19, v0
	v_mul_f32_e32 v4, v208, v4
	v_mul_f32_e32 v5, v209, v5
	v_mul_f32_e32 v6, v210, v6
	v_mul_f32_e32 v7, v211, v7
	v_xor_b32_e32 v8, 0x380, v3
	ds_write_b128 v8, v[4:7]
	v_mul_f32_e32 v12, v20, v0
	v_mul_f32_e32 v13, v21, v0
	v_mul_f32_e32 v14, v22, v0
	v_mul_f32_e32 v15, v23, v0
	v_mul_f32_e32 v12, v212, v12
	v_mul_f32_e32 v13, v213, v13
	v_mul_f32_e32 v14, v214, v14
	v_mul_f32_e32 v15, v215, v15
	v_xor_b32_e32 v8, 0x3a0, v3
	ds_write_b128 v8, v[12:15]
	s_waitcnt lgkmcnt(4)
	v_mul_f32_e32 v4, v24, v0
	v_mul_f32_e32 v5, v25, v0
	v_mul_f32_e32 v6, v26, v0
	v_mul_f32_e32 v7, v27, v0
	v_mul_f32_e32 v4, v232, v4
	v_mul_f32_e32 v5, v233, v5
	v_mul_f32_e32 v6, v234, v6
	v_mul_f32_e32 v7, v235, v7
	v_xor_b32_e32 v8, 0x3c0, v3
	ds_write_b128 v8, v[4:7]
	v_mul_f32_e32 v12, v28, v0
	v_mul_f32_e32 v13, v29, v0
	v_mul_f32_e32 v14, v30, v0
	v_mul_f32_e32 v15, v31, v0
	v_mul_f32_e32 v12, v236, v12
	v_mul_f32_e32 v13, v237, v13
	v_mul_f32_e32 v14, v238, v14
	v_mul_f32_e32 v15, v239, v15
	v_xor_b32_e32 v8, 0x3e0, v3
	ds_write_b128 v8, v[12:15]
	s_waitcnt lgkmcnt(0)
	s_mov_b64 s[4:5], 0x2000
	v_xor_b32_e32 v8, 16, v9
	ds_read_b128 v[232:235], v9 offset:0
	ds_read_b128 v[236:239], v8 offset:0
	v_xor_b32_e32 v2, 0x20, v9
	v_xor_b32_e32 v8, 0x30, v9
	ds_read_b128 v[240:243], v2 offset:2048
	ds_read_b128 v[244:247], v8 offset:2048
	v_xor_b32_e32 v2, 0x40, v9
	v_xor_b32_e32 v8, 0x50, v9
	ds_read_b128 v[208:211], v2 offset:4096
	ds_read_b128 v[212:215], v8 offset:4096
	s_waitcnt lgkmcnt(4)
	s_waitcnt vmcnt(15)
	v_lshlrev_b32_e32 v4, 16, v144
	v_and_b32_e32 v144, 0xffff0000, v144
	v_mul_f32_e32 v4, v232, v4
	v_mul_f32_e32 v144, v233, v144
	v_cvt_pk_bf16_f32 v4, v4, v144
	v_lshlrev_b32_e32 v5, 16, v145
	v_and_b32_e32 v145, 0xffff0000, v145
	v_mul_f32_e32 v5, v234, v5
	v_mul_f32_e32 v145, v235, v145
	v_cvt_pk_bf16_f32 v5, v5, v145
	v_lshlrev_b32_e32 v6, 16, v146
	v_and_b32_e32 v146, 0xffff0000, v146
	v_mul_f32_e32 v6, v236, v6
	v_mul_f32_e32 v146, v237, v146
	v_cvt_pk_bf16_f32 v6, v6, v146
	v_lshlrev_b32_e32 v7, 16, v147
	v_and_b32_e32 v147, 0xffff0000, v147
	v_mul_f32_e32 v7, v238, v7
	v_mul_f32_e32 v147, v239, v147
	v_cvt_pk_bf16_f32 v7, v7, v147
	global_store_dwordx4 v[10:11], v[4:7], off
	v_lshl_add_u64 v[10:11], v[10:11], 0, s[4:5]
	v_xor_b32_e32 v2, 0x60, v9
	v_xor_b32_e32 v8, 0x70, v9
	ds_read_b128 v[232:235], v2 offset:6144
	ds_read_b128 v[236:239], v8 offset:6144
	s_waitcnt lgkmcnt(4)
	s_waitcnt vmcnt(15)
	v_lshlrev_b32_e32 v12, 16, v148
	v_and_b32_e32 v148, 0xffff0000, v148
	v_mul_f32_e32 v12, v240, v12
	v_mul_f32_e32 v148, v241, v148
	v_cvt_pk_bf16_f32 v12, v12, v148
	v_lshlrev_b32_e32 v13, 16, v149
	v_and_b32_e32 v149, 0xffff0000, v149
	v_mul_f32_e32 v13, v242, v13
	v_mul_f32_e32 v149, v243, v149
	v_cvt_pk_bf16_f32 v13, v13, v149
	v_lshlrev_b32_e32 v14, 16, v150
	v_and_b32_e32 v150, 0xffff0000, v150
	v_mul_f32_e32 v14, v244, v14
	v_mul_f32_e32 v150, v245, v150
	v_cvt_pk_bf16_f32 v14, v14, v150
	v_lshlrev_b32_e32 v15, 16, v151
	v_and_b32_e32 v151, 0xffff0000, v151
	v_mul_f32_e32 v15, v246, v15
	v_mul_f32_e32 v151, v247, v151
	v_cvt_pk_bf16_f32 v15, v15, v151
	global_store_dwordx4 v[10:11], v[12:15], off
	v_lshl_add_u64 v[10:11], v[10:11], 0, s[4:5]
	v_xor_b32_e32 v8, 16, v9
	ds_read_b128 v[240:243], v9 offset:8192
	ds_read_b128 v[244:247], v8 offset:8192
	s_waitcnt lgkmcnt(4)
	s_waitcnt vmcnt(15)
	v_lshlrev_b32_e32 v4, 16, v152
	v_and_b32_e32 v152, 0xffff0000, v152
	v_mul_f32_e32 v4, v208, v4
	v_mul_f32_e32 v152, v209, v152
	v_cvt_pk_bf16_f32 v4, v4, v152
	v_lshlrev_b32_e32 v5, 16, v153
	v_and_b32_e32 v153, 0xffff0000, v153
	v_mul_f32_e32 v5, v210, v5
	v_mul_f32_e32 v153, v211, v153
	v_cvt_pk_bf16_f32 v5, v5, v153
	v_lshlrev_b32_e32 v6, 16, v154
	v_and_b32_e32 v154, 0xffff0000, v154
	v_mul_f32_e32 v6, v212, v6
	v_mul_f32_e32 v154, v213, v154
	v_cvt_pk_bf16_f32 v6, v6, v154
	v_lshlrev_b32_e32 v7, 16, v155
	v_and_b32_e32 v155, 0xffff0000, v155
	v_mul_f32_e32 v7, v214, v7
	v_mul_f32_e32 v155, v215, v155
	v_cvt_pk_bf16_f32 v7, v7, v155
	global_store_dwordx4 v[10:11], v[4:7], off
	v_lshl_add_u64 v[10:11], v[10:11], 0, s[4:5]
	v_xor_b32_e32 v2, 0x20, v9
	v_xor_b32_e32 v8, 0x30, v9
	ds_read_b128 v[208:211], v2 offset:10240
	ds_read_b128 v[212:215], v8 offset:10240
	s_waitcnt lgkmcnt(4)
	s_waitcnt vmcnt(15)
	v_lshlrev_b32_e32 v12, 16, v156
	v_and_b32_e32 v156, 0xffff0000, v156
	v_mul_f32_e32 v12, v232, v12
	v_mul_f32_e32 v156, v233, v156
	v_cvt_pk_bf16_f32 v12, v12, v156
	v_lshlrev_b32_e32 v13, 16, v157
	v_and_b32_e32 v157, 0xffff0000, v157
	v_mul_f32_e32 v13, v234, v13
	v_mul_f32_e32 v157, v235, v157
	v_cvt_pk_bf16_f32 v13, v13, v157
	v_lshlrev_b32_e32 v14, 16, v158
	v_and_b32_e32 v158, 0xffff0000, v158
	v_mul_f32_e32 v14, v236, v14
	v_mul_f32_e32 v158, v237, v158
	v_cvt_pk_bf16_f32 v14, v14, v158
	v_lshlrev_b32_e32 v15, 16, v159
	v_and_b32_e32 v159, 0xffff0000, v159
	v_mul_f32_e32 v15, v238, v15
	v_mul_f32_e32 v159, v239, v159
	v_cvt_pk_bf16_f32 v15, v15, v159
	global_store_dwordx4 v[10:11], v[12:15], off
	v_lshl_add_u64 v[10:11], v[10:11], 0, s[4:5]
	v_xor_b32_e32 v2, 0x40, v9
	v_xor_b32_e32 v8, 0x50, v9
	ds_read_b128 v[232:235], v2 offset:12288
	ds_read_b128 v[236:239], v8 offset:12288
	s_waitcnt lgkmcnt(4)
	s_waitcnt vmcnt(15)
	v_lshlrev_b32_e32 v4, 16, v160
	v_and_b32_e32 v160, 0xffff0000, v160
	v_mul_f32_e32 v4, v240, v4
	v_mul_f32_e32 v160, v241, v160
	v_cvt_pk_bf16_f32 v4, v4, v160
	v_lshlrev_b32_e32 v5, 16, v161
	v_and_b32_e32 v161, 0xffff0000, v161
	v_mul_f32_e32 v5, v242, v5
	v_mul_f32_e32 v161, v243, v161
	v_cvt_pk_bf16_f32 v5, v5, v161
	v_lshlrev_b32_e32 v6, 16, v162
	v_and_b32_e32 v162, 0xffff0000, v162
	v_mul_f32_e32 v6, v244, v6
	v_mul_f32_e32 v162, v245, v162
	v_cvt_pk_bf16_f32 v6, v6, v162
	v_lshlrev_b32_e32 v7, 16, v163
	v_and_b32_e32 v163, 0xffff0000, v163
	v_mul_f32_e32 v7, v246, v7
	v_mul_f32_e32 v163, v247, v163
	v_cvt_pk_bf16_f32 v7, v7, v163
	global_store_dwordx4 v[10:11], v[4:7], off
	v_lshl_add_u64 v[10:11], v[10:11], 0, s[4:5]
	v_xor_b32_e32 v2, 0x60, v9
	v_xor_b32_e32 v8, 0x70, v9
	ds_read_b128 v[240:243], v2 offset:14336
	ds_read_b128 v[244:247], v8 offset:14336
	s_waitcnt lgkmcnt(4)
	s_waitcnt vmcnt(15)
	v_lshlrev_b32_e32 v12, 16, v164
	v_and_b32_e32 v164, 0xffff0000, v164
	v_mul_f32_e32 v12, v208, v12
	v_mul_f32_e32 v164, v209, v164
	v_cvt_pk_bf16_f32 v12, v12, v164
	v_lshlrev_b32_e32 v13, 16, v165
	v_and_b32_e32 v165, 0xffff0000, v165
	v_mul_f32_e32 v13, v210, v13
	v_mul_f32_e32 v165, v211, v165
	v_cvt_pk_bf16_f32 v13, v13, v165
	v_lshlrev_b32_e32 v14, 16, v166
	v_and_b32_e32 v166, 0xffff0000, v166
	v_mul_f32_e32 v14, v212, v14
	v_mul_f32_e32 v166, v213, v166
	v_cvt_pk_bf16_f32 v14, v14, v166
	v_lshlrev_b32_e32 v15, 16, v167
	v_and_b32_e32 v167, 0xffff0000, v167
	v_mul_f32_e32 v15, v214, v15
	v_mul_f32_e32 v167, v215, v167
	v_cvt_pk_bf16_f32 v15, v15, v167
	global_store_dwordx4 v[10:11], v[12:15], off
	v_lshl_add_u64 v[10:11], v[10:11], 0, s[4:5]
	v_xor_b32_e32 v8, 16, v9
	ds_read_b128 v[208:211], v9 offset:16384
	ds_read_b128 v[212:215], v8 offset:16384
	s_waitcnt lgkmcnt(4)
	s_waitcnt vmcnt(15)
	v_lshlrev_b32_e32 v4, 16, v168
	v_and_b32_e32 v168, 0xffff0000, v168
	v_mul_f32_e32 v4, v232, v4
	v_mul_f32_e32 v168, v233, v168
	v_cvt_pk_bf16_f32 v4, v4, v168
	v_lshlrev_b32_e32 v5, 16, v169
	v_and_b32_e32 v169, 0xffff0000, v169
	v_mul_f32_e32 v5, v234, v5
	v_mul_f32_e32 v169, v235, v169
	v_cvt_pk_bf16_f32 v5, v5, v169
	v_lshlrev_b32_e32 v6, 16, v170
	v_and_b32_e32 v170, 0xffff0000, v170
	v_mul_f32_e32 v6, v236, v6
	v_mul_f32_e32 v170, v237, v170
	v_cvt_pk_bf16_f32 v6, v6, v170
	v_lshlrev_b32_e32 v7, 16, v171
	v_and_b32_e32 v171, 0xffff0000, v171
	v_mul_f32_e32 v7, v238, v7
	v_mul_f32_e32 v171, v239, v171
	v_cvt_pk_bf16_f32 v7, v7, v171
	global_store_dwordx4 v[10:11], v[4:7], off
	v_lshl_add_u64 v[10:11], v[10:11], 0, s[4:5]
	v_xor_b32_e32 v2, 0x20, v9
	v_xor_b32_e32 v8, 0x30, v9
	ds_read_b128 v[232:235], v2 offset:18432
	ds_read_b128 v[236:239], v8 offset:18432
	s_waitcnt lgkmcnt(4)
	s_waitcnt vmcnt(15)
	v_lshlrev_b32_e32 v12, 16, v172
	v_and_b32_e32 v172, 0xffff0000, v172
	v_mul_f32_e32 v12, v240, v12
	v_mul_f32_e32 v172, v241, v172
	v_cvt_pk_bf16_f32 v12, v12, v172
	v_lshlrev_b32_e32 v13, 16, v173
	v_and_b32_e32 v173, 0xffff0000, v173
	v_mul_f32_e32 v13, v242, v13
	v_mul_f32_e32 v173, v243, v173
	v_cvt_pk_bf16_f32 v13, v13, v173
	v_lshlrev_b32_e32 v14, 16, v174
	v_and_b32_e32 v174, 0xffff0000, v174
	v_mul_f32_e32 v14, v244, v14
	v_mul_f32_e32 v174, v245, v174
	v_cvt_pk_bf16_f32 v14, v14, v174
	v_lshlrev_b32_e32 v15, 16, v175
	v_and_b32_e32 v175, 0xffff0000, v175
	v_mul_f32_e32 v15, v246, v15
	v_mul_f32_e32 v175, v247, v175
	v_cvt_pk_bf16_f32 v15, v15, v175
	global_store_dwordx4 v[10:11], v[12:15], off
	v_lshl_add_u64 v[10:11], v[10:11], 0, s[4:5]
	v_xor_b32_e32 v2, 0x40, v9
	v_xor_b32_e32 v8, 0x50, v9
	ds_read_b128 v[240:243], v2 offset:20480
	ds_read_b128 v[244:247], v8 offset:20480
	s_waitcnt lgkmcnt(4)
	s_waitcnt vmcnt(15)
	v_lshlrev_b32_e32 v4, 16, v176
	v_and_b32_e32 v176, 0xffff0000, v176
	v_mul_f32_e32 v4, v208, v4
	v_mul_f32_e32 v176, v209, v176
	v_cvt_pk_bf16_f32 v4, v4, v176
	v_lshlrev_b32_e32 v5, 16, v177
	v_and_b32_e32 v177, 0xffff0000, v177
	v_mul_f32_e32 v5, v210, v5
	v_mul_f32_e32 v177, v211, v177
	v_cvt_pk_bf16_f32 v5, v5, v177
	v_lshlrev_b32_e32 v6, 16, v178
	v_and_b32_e32 v178, 0xffff0000, v178
	v_mul_f32_e32 v6, v212, v6
	v_mul_f32_e32 v178, v213, v178
	v_cvt_pk_bf16_f32 v6, v6, v178
	v_lshlrev_b32_e32 v7, 16, v179
	v_and_b32_e32 v179, 0xffff0000, v179
	v_mul_f32_e32 v7, v214, v7
	v_mul_f32_e32 v179, v215, v179
	v_cvt_pk_bf16_f32 v7, v7, v179
	global_store_dwordx4 v[10:11], v[4:7], off
	v_lshl_add_u64 v[10:11], v[10:11], 0, s[4:5]
	v_xor_b32_e32 v2, 0x60, v9
	v_xor_b32_e32 v8, 0x70, v9
	ds_read_b128 v[208:211], v2 offset:22528
	ds_read_b128 v[212:215], v8 offset:22528
	s_waitcnt lgkmcnt(4)
	s_waitcnt vmcnt(15)
	v_lshlrev_b32_e32 v12, 16, v180
	v_and_b32_e32 v180, 0xffff0000, v180
	v_mul_f32_e32 v12, v232, v12
	v_mul_f32_e32 v180, v233, v180
	v_cvt_pk_bf16_f32 v12, v12, v180
	v_lshlrev_b32_e32 v13, 16, v181
	v_and_b32_e32 v181, 0xffff0000, v181
	v_mul_f32_e32 v13, v234, v13
	v_mul_f32_e32 v181, v235, v181
	v_cvt_pk_bf16_f32 v13, v13, v181
	v_lshlrev_b32_e32 v14, 16, v182
	v_and_b32_e32 v182, 0xffff0000, v182
	v_mul_f32_e32 v14, v236, v14
	v_mul_f32_e32 v182, v237, v182
	v_cvt_pk_bf16_f32 v14, v14, v182
	v_lshlrev_b32_e32 v15, 16, v183
	v_and_b32_e32 v183, 0xffff0000, v183
	v_mul_f32_e32 v15, v238, v15
	v_mul_f32_e32 v183, v239, v183
	v_cvt_pk_bf16_f32 v15, v15, v183
	global_store_dwordx4 v[10:11], v[12:15], off
	v_lshl_add_u64 v[10:11], v[10:11], 0, s[4:5]
	v_xor_b32_e32 v8, 16, v9
	ds_read_b128 v[232:235], v9 offset:24576
	ds_read_b128 v[236:239], v8 offset:24576
	s_waitcnt lgkmcnt(4)
	s_waitcnt vmcnt(15)
	v_lshlrev_b32_e32 v4, 16, v184
	v_and_b32_e32 v184, 0xffff0000, v184
	v_mul_f32_e32 v4, v240, v4
	v_mul_f32_e32 v184, v241, v184
	v_cvt_pk_bf16_f32 v4, v4, v184
	v_lshlrev_b32_e32 v5, 16, v185
	v_and_b32_e32 v185, 0xffff0000, v185
	v_mul_f32_e32 v5, v242, v5
	v_mul_f32_e32 v185, v243, v185
	v_cvt_pk_bf16_f32 v5, v5, v185
	v_lshlrev_b32_e32 v6, 16, v186
	v_and_b32_e32 v186, 0xffff0000, v186
	v_mul_f32_e32 v6, v244, v6
	v_mul_f32_e32 v186, v245, v186
	v_cvt_pk_bf16_f32 v6, v6, v186
	v_lshlrev_b32_e32 v7, 16, v187
	v_and_b32_e32 v187, 0xffff0000, v187
	v_mul_f32_e32 v7, v246, v7
	v_mul_f32_e32 v187, v247, v187
	v_cvt_pk_bf16_f32 v7, v7, v187
	global_store_dwordx4 v[10:11], v[4:7], off
	v_lshl_add_u64 v[10:11], v[10:11], 0, s[4:5]
	v_xor_b32_e32 v2, 0x20, v9
	v_xor_b32_e32 v8, 0x30, v9
	ds_read_b128 v[240:243], v2 offset:26624
	ds_read_b128 v[244:247], v8 offset:26624
	s_waitcnt lgkmcnt(4)
	s_waitcnt vmcnt(15)
	v_lshlrev_b32_e32 v12, 16, v188
	v_and_b32_e32 v188, 0xffff0000, v188
	v_mul_f32_e32 v12, v208, v12
	v_mul_f32_e32 v188, v209, v188
	v_cvt_pk_bf16_f32 v12, v12, v188
	v_lshlrev_b32_e32 v13, 16, v189
	v_and_b32_e32 v189, 0xffff0000, v189
	v_mul_f32_e32 v13, v210, v13
	v_mul_f32_e32 v189, v211, v189
	v_cvt_pk_bf16_f32 v13, v13, v189
	v_lshlrev_b32_e32 v14, 16, v190
	v_and_b32_e32 v190, 0xffff0000, v190
	v_mul_f32_e32 v14, v212, v14
	v_mul_f32_e32 v190, v213, v190
	v_cvt_pk_bf16_f32 v14, v14, v190
	v_lshlrev_b32_e32 v15, 16, v191
	v_and_b32_e32 v191, 0xffff0000, v191
	v_mul_f32_e32 v15, v214, v15
	v_mul_f32_e32 v191, v215, v191
	v_cvt_pk_bf16_f32 v15, v15, v191
	global_store_dwordx4 v[10:11], v[12:15], off
	v_lshl_add_u64 v[10:11], v[10:11], 0, s[4:5]
	v_xor_b32_e32 v2, 0x40, v9
	v_xor_b32_e32 v8, 0x50, v9
	ds_read_b128 v[208:211], v2 offset:28672
	ds_read_b128 v[212:215], v8 offset:28672
	s_waitcnt lgkmcnt(4)
	s_waitcnt vmcnt(15)
	v_lshlrev_b32_e32 v4, 16, v216
	v_and_b32_e32 v216, 0xffff0000, v216
	v_mul_f32_e32 v4, v232, v4
	v_mul_f32_e32 v216, v233, v216
	v_cvt_pk_bf16_f32 v4, v4, v216
	v_lshlrev_b32_e32 v5, 16, v217
	v_and_b32_e32 v217, 0xffff0000, v217
	v_mul_f32_e32 v5, v234, v5
	v_mul_f32_e32 v217, v235, v217
	v_cvt_pk_bf16_f32 v5, v5, v217
	v_lshlrev_b32_e32 v6, 16, v218
	v_and_b32_e32 v218, 0xffff0000, v218
	v_mul_f32_e32 v6, v236, v6
	v_mul_f32_e32 v218, v237, v218
	v_cvt_pk_bf16_f32 v6, v6, v218
	v_lshlrev_b32_e32 v7, 16, v219
	v_and_b32_e32 v219, 0xffff0000, v219
	v_mul_f32_e32 v7, v238, v7
	v_mul_f32_e32 v219, v239, v219
	v_cvt_pk_bf16_f32 v7, v7, v219
	global_store_dwordx4 v[10:11], v[4:7], off
	v_lshl_add_u64 v[10:11], v[10:11], 0, s[4:5]
	v_xor_b32_e32 v2, 0x60, v9
	v_xor_b32_e32 v8, 0x70, v9
	ds_read_b128 v[232:235], v2 offset:30720
	ds_read_b128 v[236:239], v8 offset:30720
	s_waitcnt lgkmcnt(4)
	s_waitcnt vmcnt(15)
	v_lshlrev_b32_e32 v12, 16, v220
	v_and_b32_e32 v220, 0xffff0000, v220
	v_mul_f32_e32 v12, v240, v12
	v_mul_f32_e32 v220, v241, v220
	v_cvt_pk_bf16_f32 v12, v12, v220
	v_lshlrev_b32_e32 v13, 16, v221
	v_and_b32_e32 v221, 0xffff0000, v221
	v_mul_f32_e32 v13, v242, v13
	v_mul_f32_e32 v221, v243, v221
	v_cvt_pk_bf16_f32 v13, v13, v221
	v_lshlrev_b32_e32 v14, 16, v222
	v_and_b32_e32 v222, 0xffff0000, v222
	v_mul_f32_e32 v14, v244, v14
	v_mul_f32_e32 v222, v245, v222
	v_cvt_pk_bf16_f32 v14, v14, v222
	v_lshlrev_b32_e32 v15, 16, v223
	v_and_b32_e32 v223, 0xffff0000, v223
	v_mul_f32_e32 v15, v246, v15
	v_mul_f32_e32 v223, v247, v223
	v_cvt_pk_bf16_f32 v15, v15, v223
	global_store_dwordx4 v[10:11], v[12:15], off
	v_lshl_add_u64 v[10:11], v[10:11], 0, s[4:5]
	s_waitcnt lgkmcnt(2)
	s_waitcnt vmcnt(15)
	v_lshlrev_b32_e32 v4, 16, v224
	v_and_b32_e32 v224, 0xffff0000, v224
	v_mul_f32_e32 v4, v208, v4
	v_mul_f32_e32 v224, v209, v224
	v_cvt_pk_bf16_f32 v4, v4, v224
	v_lshlrev_b32_e32 v5, 16, v225
	v_and_b32_e32 v225, 0xffff0000, v225
	v_mul_f32_e32 v5, v210, v5
	v_mul_f32_e32 v225, v211, v225
	v_cvt_pk_bf16_f32 v5, v5, v225
	v_lshlrev_b32_e32 v6, 16, v226
	v_and_b32_e32 v226, 0xffff0000, v226
	v_mul_f32_e32 v6, v212, v6
	v_mul_f32_e32 v226, v213, v226
	v_cvt_pk_bf16_f32 v6, v6, v226
	v_lshlrev_b32_e32 v7, 16, v227
	v_and_b32_e32 v227, 0xffff0000, v227
	v_mul_f32_e32 v7, v214, v7
	v_mul_f32_e32 v227, v215, v227
	v_cvt_pk_bf16_f32 v7, v7, v227
	global_store_dwordx4 v[10:11], v[4:7], off
	v_lshl_add_u64 v[10:11], v[10:11], 0, s[4:5]
	s_waitcnt lgkmcnt(0)
	s_waitcnt vmcnt(15)
	v_lshlrev_b32_e32 v12, 16, v228
	v_and_b32_e32 v228, 0xffff0000, v228
	v_mul_f32_e32 v12, v232, v12
	v_mul_f32_e32 v228, v233, v228
	v_cvt_pk_bf16_f32 v12, v12, v228
	v_lshlrev_b32_e32 v13, 16, v229
	v_and_b32_e32 v229, 0xffff0000, v229
	v_mul_f32_e32 v13, v234, v13
	v_mul_f32_e32 v229, v235, v229
	v_cvt_pk_bf16_f32 v13, v13, v229
	v_lshlrev_b32_e32 v14, 16, v230
	v_and_b32_e32 v230, 0xffff0000, v230
	v_mul_f32_e32 v14, v236, v14
	v_mul_f32_e32 v230, v237, v230
	v_cvt_pk_bf16_f32 v14, v14, v230
	v_lshlrev_b32_e32 v15, 16, v231
	v_and_b32_e32 v231, 0xffff0000, v231
	v_mul_f32_e32 v15, v238, v15
	v_mul_f32_e32 v231, v239, v231
	v_cvt_pk_bf16_f32 v15, v15, v231
	global_store_dwordx4 v[10:11], v[12:15], off
	s_branch .LBB0_306

.LBB0_1279:
	s_lshl_b32 s15, s54, 8
	s_add_i32 s15, s15, s79
	v_mbcnt_lo_u32_b32 v156, -1, 0
	v_mbcnt_hi_u32_b32 v156, -1, v156
	v_readlane_b32 s17, v252, 33
	v_and_or_b32 v140, v156, 15, s15
	s_lshl_b32 s15, s53, 8
	v_ashrrev_i32_e32 v141, 1, v156
	s_or_b32 s15, s15, s17
	v_and_b32_e32 v141, -8, v141
	v_add_u32_e32 v146, s15, v141
	v_ashrrev_i32_e32 v141, 31, v140
	v_ashrrev_i32_e32 v147, 31, v146
	v_lshlrev_b64 v[142:143], 11, v[140:141]
	v_lshl_add_u64 v[144:145], v[142:143], 0, v[146:147]
	v_lshlrev_b64 v[142:143], 2, v[144:145]
	v_lshl_add_u64 v[150:151], s[0:1], 0, v[142:143]
	global_load_dwordx4 v[158:161], v[150:151], off offset:16 nt
	global_load_dwordx4 v[162:165], v[150:151], off nt
	v_lshl_add_u64 v[152:153], s[10:11], 0, v[142:143]
	v_cndmask_b32_e64 v142, 0, 1, s[12:13]
	v_cmp_ne_u32_e64 s[92:93], 1, v142
	s_andn2_b64 vcc, exec, s[12:13]
	v_lshl_add_u64 v[142:143], v[146:147], 2, s[4:5]
	v_lshl_add_u64 v[148:149], v[144:145], 1, s[6:7]
	s_waitcnt vmcnt(0)
	v_pk_add_f32 v[124:125], v[124:125], v[160:161]
	v_pk_add_f32 v[128:129], v[128:129], v[164:165]
	v_pk_add_f32 v[126:127], v[126:127], v[162:163]
	v_pk_add_f32 v[122:123], v[122:123], v[158:159]
	global_store_dwordx4 v[152:153], v[126:129], off
	global_store_dwordx4 v[152:153], v[122:125], off offset:16
	s_cbranch_vccnz .LBB0_1281
	global_load_dwordx4 v[234:237], v[142:143], off offset:16
	global_load_dwordx4 v[230:233], v[142:143], off
	global_load_dwordx4 v[242:245], v[142:143], off offset:528
	global_load_dwordx4 v[238:241], v[142:143], off offset:512
	s_waitcnt vmcnt(0)
	v_mov_b32_e32 v158, v234
	v_mov_b32_e32 v159, v235
	v_mov_b32_e32 v160, v236
	v_mov_b32_e32 v161, v237
	v_mov_b32_e32 v162, v230
	v_mov_b32_e32 v163, v231
	v_mov_b32_e32 v164, v232
	v_mov_b32_e32 v165, v233
	v_pk_mul_f32 v[166:167], v[124:125], v[160:161]
	v_pk_mul_f32 v[162:163], v[126:127], v[162:163]
	v_pk_mul_f32 v[126:127], v[126:127], v[126:127]
	v_pk_mul_f32 v[164:165], v[128:129], v[164:165]
	v_pk_mul_f32 v[128:129], v[128:129], v[128:129]
	v_add_f32_e32 v126, v126, v127
	v_add_f32_e32 v126, v128, v126
	v_pk_mul_f32 v[160:161], v[122:123], v[158:159]
	v_pk_mul_f32 v[122:123], v[122:123], v[122:123]
	v_add_f32_e32 v126, v129, v126
	v_add_f32_e32 v122, v122, v126
	v_pk_mul_f32 v[124:125], v[124:125], v[124:125]
	v_add_f32_e32 v122, v123, v122
	v_add_f32_e32 v122, v124, v122
	v_add_f32_e32 v122, v125, v122
	v_cvt_pk_bf16_f32 v158, v162, v163
	v_cvt_pk_bf16_f32 v159, v164, v165
	v_cvt_pk_bf16_f32 v160, v160, v161
	v_cvt_pk_bf16_f32 v161, v166, v167
	global_store_dwordx4 v[148:149], v[158:161], off
	s_branch .LBB0_1282

.LBB0_1282:
	v_cmp_gt_u32_e64 s[90:91], 16, v156
	global_load_dwordx4 v[124:127], v[150:151], off offset:528 nt
	global_load_dwordx4 v[156:159], v[150:151], off offset:512 nt
	s_and_b64 vcc, exec, s[92:93]
	s_waitcnt vmcnt(1)
	v_pk_add_f32 v[116:117], v[116:117], v[126:127]
	s_waitcnt vmcnt(0)
	v_pk_add_f32 v[120:121], v[120:121], v[158:159]
	v_pk_add_f32 v[118:119], v[118:119], v[156:157]
	v_pk_add_f32 v[114:115], v[114:115], v[124:125]
	global_store_dwordx4 v[152:153], v[118:121], off offset:512
	global_store_dwordx4 v[152:153], v[114:117], off offset:528
	s_cbranch_vccnz .LBB0_1286
	v_mov_b32_e32 v124, v242
	v_mov_b32_e32 v125, v243
	v_mov_b32_e32 v126, v244
	v_mov_b32_e32 v127, v245
	v_mov_b32_e32 v150, v238
	v_mov_b32_e32 v151, v239
	v_mov_b32_e32 v152, v240
	v_mov_b32_e32 v153, v241
	v_pk_mul_f32 v[150:151], v[118:119], v[150:151]
	v_mul_f32_e32 v119, v119, v119
	v_fmac_f32_e32 v119, v118, v118
	v_fmac_f32_e32 v119, v120, v120
	v_fmac_f32_e32 v119, v121, v121
	v_fmac_f32_e32 v119, v114, v114
	v_fmac_f32_e32 v119, v115, v115
	v_pk_mul_f32 v[128:129], v[120:121], v[152:153]
	v_pk_mul_f32 v[152:153], v[116:117], v[126:127]
	v_fmac_f32_e32 v119, v116, v116
	v_and_b32_e32 v116, 64, v200
	v_pk_mul_f32 v[126:127], v[114:115], v[124:125]
	v_xor_b32_e32 v115, 16, v200
	v_add_u32_e32 v116, 64, v116
	v_cmp_lt_i32_e32 vcc, v115, v116
	v_fmac_f32_e32 v119, v117, v117
	v_add_f32_e32 v114, v122, v119
	v_cndmask_b32_e32 v115, v200, v115, vcc
	v_lshlrev_b32_e32 v115, 2, v115
	ds_bpermute_b32 v115, v115, v114
	v_cvt_pk_bf16_f32 v124, v150, v151
	v_cvt_pk_bf16_f32 v125, v128, v129
	v_cvt_pk_bf16_f32 v126, v126, v127
	v_cvt_pk_bf16_f32 v127, v152, v153
	s_waitcnt lgkmcnt(0)
	v_add_f32_e32 v114, v114, v115
	v_xor_b32_e32 v115, 32, v200
	v_cmp_lt_i32_e32 vcc, v115, v116
	global_store_dwordx4 v[148:149], v[124:127], off offset:256
	s_nop 0
	v_cndmask_b32_e32 v115, v200, v115, vcc
	v_lshlrev_b32_e32 v115, 2, v115
	ds_bpermute_b32 v115, v115, v114
	s_and_saveexec_b64 s[22:23], s[90:91]
	s_cbranch_execz .LBB0_1285
	v_lshl_add_u64 v[116:117], v[140:141], 2, s[8:9]
	s_waitcnt lgkmcnt(0)
	v_add_f32_e32 v114, v114, v115
	global_atomic_add_f32 v[116:117], v114, off

.LBB0_1286:
	s_nop 0
	v_or_b32_e32 v114, 16, v140
	s_waitcnt lgkmcnt(0)
	v_ashrrev_i32_e32 v115, 31, v114
	v_lshlrev_b64 v[114:115], 11, v[114:115]
	v_lshl_add_u64 v[114:115], v[114:115], 0, v[146:147]
	v_lshlrev_b64 v[116:117], 2, v[114:115]
	v_lshl_add_u64 v[118:119], s[0:1], 0, v[116:117]
	global_load_dwordx4 v[120:123], v[118:119], off nt
	global_load_dwordx4 v[124:127], v[118:119], off offset:16 nt
	s_and_b64 vcc, exec, s[92:93]
	v_lshl_add_u64 v[116:117], s[10:11], 0, v[116:117]
	v_lshl_add_u64 v[114:115], v[114:115], 1, s[6:7]
	s_waitcnt vmcnt(1)
	v_pk_add_f32 v[112:113], v[112:113], v[122:123]
	v_pk_add_f32 v[110:111], v[110:111], v[120:121]
	s_waitcnt vmcnt(0)
	v_pk_add_f32 v[108:109], v[108:109], v[126:127]
	v_pk_add_f32 v[106:107], v[106:107], v[124:125]
	global_store_dwordx4 v[116:117], v[110:113], off
	global_store_dwordx4 v[116:117], v[106:109], off offset:16
	s_cbranch_vccnz .LBB0_1288
	v_mov_b32_e32 v120, v234
	v_mov_b32_e32 v121, v235
	v_mov_b32_e32 v122, v236
	v_mov_b32_e32 v123, v237
	v_mov_b32_e32 v124, v230
	v_mov_b32_e32 v125, v231
	v_mov_b32_e32 v126, v232
	v_mov_b32_e32 v127, v233
	v_pk_mul_f32 v[128:129], v[108:109], v[122:123]
	v_pk_mul_f32 v[124:125], v[110:111], v[124:125]
	v_pk_mul_f32 v[110:111], v[110:111], v[110:111]
	v_pk_mul_f32 v[126:127], v[112:113], v[126:127]
	v_pk_mul_f32 v[112:113], v[112:113], v[112:113]
	v_add_f32_e32 v110, v110, v111
	v_add_f32_e32 v110, v112, v110
	v_pk_mul_f32 v[122:123], v[106:107], v[120:121]
	v_pk_mul_f32 v[106:107], v[106:107], v[106:107]
	v_add_f32_e32 v110, v113, v110
	v_add_f32_e32 v106, v106, v110
	v_pk_mul_f32 v[108:109], v[108:109], v[108:109]
	v_add_f32_e32 v106, v107, v106
	v_add_f32_e32 v106, v108, v106
	v_add_f32_e32 v106, v109, v106
	v_cvt_pk_bf16_f32 v120, v124, v125
	v_cvt_pk_bf16_f32 v121, v126, v127
	v_cvt_pk_bf16_f32 v122, v122, v123
	v_cvt_pk_bf16_f32 v123, v128, v129
	global_store_dwordx4 v[114:115], v[120:123], off
	s_branch .LBB0_1289

.LBB0_1289:
	global_load_dwordx4 v[108:111], v[118:119], off offset:512 nt
	s_nop 0
	global_load_dwordx4 v[118:121], v[118:119], off offset:528 nt
	s_and_b64 vcc, exec, s[92:93]
	s_waitcnt vmcnt(1)
	v_pk_add_f32 v[104:105], v[104:105], v[110:111]
	v_pk_add_f32 v[102:103], v[102:103], v[108:109]
	s_waitcnt vmcnt(0)
	v_pk_add_f32 v[100:101], v[100:101], v[120:121]
	v_pk_add_f32 v[98:99], v[98:99], v[118:119]
	global_store_dwordx4 v[116:117], v[102:105], off offset:512
	global_store_dwordx4 v[116:117], v[98:101], off offset:528
	s_cbranch_vccnz .LBB0_1293
	v_mov_b32_e32 v108, v242
	v_mov_b32_e32 v109, v243
	v_mov_b32_e32 v110, v244
	v_mov_b32_e32 v111, v245
	v_mov_b32_e32 v116, v238
	v_mov_b32_e32 v117, v239
	v_mov_b32_e32 v118, v240
	v_mov_b32_e32 v119, v241
	v_pk_mul_f32 v[116:117], v[102:103], v[116:117]
	v_mul_f32_e32 v103, v103, v103
	v_fmac_f32_e32 v103, v102, v102
	v_fmac_f32_e32 v103, v104, v104
	v_fmac_f32_e32 v103, v105, v105
	v_fmac_f32_e32 v103, v98, v98
	v_fmac_f32_e32 v103, v99, v99
	v_pk_mul_f32 v[112:113], v[104:105], v[118:119]
	v_pk_mul_f32 v[118:119], v[100:101], v[110:111]
	v_fmac_f32_e32 v103, v100, v100
	v_and_b32_e32 v100, 64, v200
	v_pk_mul_f32 v[110:111], v[98:99], v[108:109]
	v_xor_b32_e32 v99, 16, v200
	v_add_u32_e32 v100, 64, v100
	v_cmp_lt_i32_e32 vcc, v99, v100
	v_fmac_f32_e32 v103, v101, v101
	v_add_f32_e32 v98, v106, v103
	v_cndmask_b32_e32 v99, v200, v99, vcc
	v_lshlrev_b32_e32 v99, 2, v99
	ds_bpermute_b32 v99, v99, v98
	v_cvt_pk_bf16_f32 v108, v116, v117
	v_cvt_pk_bf16_f32 v109, v112, v113
	v_cvt_pk_bf16_f32 v110, v110, v111
	v_cvt_pk_bf16_f32 v111, v118, v119
	s_waitcnt lgkmcnt(0)
	v_add_f32_e32 v98, v98, v99
	v_xor_b32_e32 v99, 32, v200
	v_cmp_lt_i32_e32 vcc, v99, v100
	global_store_dwordx4 v[114:115], v[108:111], off offset:256
	s_nop 0
	v_cndmask_b32_e32 v99, v200, v99, vcc
	v_lshlrev_b32_e32 v99, 2, v99
	ds_bpermute_b32 v99, v99, v98
	s_and_saveexec_b64 s[22:23], s[90:91]
	s_cbranch_execz .LBB0_1292
	v_lshl_add_u64 v[100:101], v[140:141], 2, s[8:9]
	s_waitcnt lgkmcnt(0)
	v_add_f32_e32 v98, v98, v99
	global_atomic_add_f32 v[100:101], v98, off offset:64

.LBB0_1293:
	s_nop 0
	v_or_b32_e32 v98, 32, v140
	s_waitcnt lgkmcnt(0)
	v_ashrrev_i32_e32 v99, 31, v98
	v_lshlrev_b64 v[98:99], 11, v[98:99]
	v_lshl_add_u64 v[98:99], v[98:99], 0, v[146:147]
	v_lshlrev_b64 v[100:101], 2, v[98:99]
	v_lshl_add_u64 v[102:103], s[0:1], 0, v[100:101]
	global_load_dwordx4 v[104:107], v[102:103], off nt
	global_load_dwordx4 v[108:111], v[102:103], off offset:16 nt
	s_and_b64 vcc, exec, s[92:93]
	v_lshl_add_u64 v[100:101], s[10:11], 0, v[100:101]
	v_lshl_add_u64 v[98:99], v[98:99], 1, s[6:7]
	s_waitcnt vmcnt(1)
	v_pk_add_f32 v[96:97], v[96:97], v[106:107]
	v_pk_add_f32 v[94:95], v[94:95], v[104:105]
	s_waitcnt vmcnt(0)
	v_pk_add_f32 v[92:93], v[92:93], v[110:111]
	v_pk_add_f32 v[90:91], v[90:91], v[108:109]
	global_store_dwordx4 v[100:101], v[94:97], off
	global_store_dwordx4 v[100:101], v[90:93], off offset:16
	s_cbranch_vccnz .LBB0_1295
	v_mov_b32_e32 v104, v234
	v_mov_b32_e32 v105, v235
	v_mov_b32_e32 v106, v236
	v_mov_b32_e32 v107, v237
	v_mov_b32_e32 v108, v230
	v_mov_b32_e32 v109, v231
	v_mov_b32_e32 v110, v232
	v_mov_b32_e32 v111, v233
	v_pk_mul_f32 v[112:113], v[92:93], v[106:107]
	v_pk_mul_f32 v[108:109], v[94:95], v[108:109]
	v_pk_mul_f32 v[94:95], v[94:95], v[94:95]
	v_pk_mul_f32 v[110:111], v[96:97], v[110:111]
	v_pk_mul_f32 v[96:97], v[96:97], v[96:97]
	v_add_f32_e32 v94, v94, v95
	v_add_f32_e32 v94, v96, v94
	v_pk_mul_f32 v[106:107], v[90:91], v[104:105]
	v_pk_mul_f32 v[90:91], v[90:91], v[90:91]
	v_add_f32_e32 v94, v97, v94
	v_add_f32_e32 v90, v90, v94
	v_pk_mul_f32 v[92:93], v[92:93], v[92:93]
	v_add_f32_e32 v90, v91, v90
	v_add_f32_e32 v90, v92, v90
	v_add_f32_e32 v90, v93, v90
	v_cvt_pk_bf16_f32 v104, v108, v109
	v_cvt_pk_bf16_f32 v105, v110, v111
	v_cvt_pk_bf16_f32 v106, v106, v107
	v_cvt_pk_bf16_f32 v107, v112, v113
	global_store_dwordx4 v[98:99], v[104:107], off
	s_branch .LBB0_1296

.LBB0_1296:
	global_load_dwordx4 v[92:95], v[102:103], off offset:512 nt
	s_nop 0
	global_load_dwordx4 v[102:105], v[102:103], off offset:528 nt
	s_and_b64 vcc, exec, s[92:93]
	s_waitcnt vmcnt(1)
	v_pk_add_f32 v[88:89], v[88:89], v[94:95]
	v_pk_add_f32 v[86:87], v[86:87], v[92:93]
	s_waitcnt vmcnt(0)
	v_pk_add_f32 v[84:85], v[84:85], v[104:105]
	v_pk_add_f32 v[82:83], v[82:83], v[102:103]
	global_store_dwordx4 v[100:101], v[86:89], off offset:512
	global_store_dwordx4 v[100:101], v[82:85], off offset:528
	s_cbranch_vccnz .LBB0_1300
	v_mov_b32_e32 v92, v242
	v_mov_b32_e32 v93, v243
	v_mov_b32_e32 v94, v244
	v_mov_b32_e32 v95, v245
	v_mov_b32_e32 v100, v238
	v_mov_b32_e32 v101, v239
	v_mov_b32_e32 v102, v240
	v_mov_b32_e32 v103, v241
	v_pk_mul_f32 v[100:101], v[86:87], v[100:101]
	v_mul_f32_e32 v87, v87, v87
	v_fmac_f32_e32 v87, v86, v86
	v_fmac_f32_e32 v87, v88, v88
	v_fmac_f32_e32 v87, v89, v89
	v_fmac_f32_e32 v87, v82, v82
	v_fmac_f32_e32 v87, v83, v83
	v_pk_mul_f32 v[96:97], v[88:89], v[102:103]
	v_pk_mul_f32 v[102:103], v[84:85], v[94:95]
	v_fmac_f32_e32 v87, v84, v84
	v_and_b32_e32 v84, 64, v200
	v_pk_mul_f32 v[94:95], v[82:83], v[92:93]
	v_xor_b32_e32 v83, 16, v200
	v_add_u32_e32 v84, 64, v84
	v_cmp_lt_i32_e32 vcc, v83, v84
	v_fmac_f32_e32 v87, v85, v85
	v_add_f32_e32 v82, v90, v87
	v_cndmask_b32_e32 v83, v200, v83, vcc
	v_lshlrev_b32_e32 v83, 2, v83
	ds_bpermute_b32 v83, v83, v82
	v_cvt_pk_bf16_f32 v92, v100, v101
	v_cvt_pk_bf16_f32 v93, v96, v97
	v_cvt_pk_bf16_f32 v94, v94, v95
	v_cvt_pk_bf16_f32 v95, v102, v103
	s_waitcnt lgkmcnt(0)
	v_add_f32_e32 v82, v82, v83
	v_xor_b32_e32 v83, 32, v200
	v_cmp_lt_i32_e32 vcc, v83, v84
	global_store_dwordx4 v[98:99], v[92:95], off offset:256
	s_nop 0
	v_cndmask_b32_e32 v83, v200, v83, vcc
	v_lshlrev_b32_e32 v83, 2, v83
	ds_bpermute_b32 v83, v83, v82
	s_and_saveexec_b64 s[22:23], s[90:91]
	s_cbranch_execz .LBB0_1299
	v_lshl_add_u64 v[84:85], v[140:141], 2, s[8:9]
	s_waitcnt lgkmcnt(0)
	v_add_f32_e32 v82, v82, v83
	global_atomic_add_f32 v[84:85], v82, off offset:128

.LBB0_1300:
	s_nop 0
	v_or_b32_e32 v82, 48, v140
	s_waitcnt lgkmcnt(0)
	v_ashrrev_i32_e32 v83, 31, v82
	v_lshlrev_b64 v[82:83], 11, v[82:83]
	v_lshl_add_u64 v[82:83], v[82:83], 0, v[146:147]
	v_lshlrev_b64 v[84:85], 2, v[82:83]
	v_lshl_add_u64 v[86:87], s[0:1], 0, v[84:85]
	global_load_dwordx4 v[88:91], v[86:87], off nt
	global_load_dwordx4 v[92:95], v[86:87], off offset:16 nt
	s_and_b64 vcc, exec, s[92:93]
	v_lshl_add_u64 v[84:85], s[10:11], 0, v[84:85]
	v_lshl_add_u64 v[82:83], v[82:83], 1, s[6:7]
	s_waitcnt vmcnt(1)
	v_pk_add_f32 v[80:81], v[80:81], v[90:91]
	v_pk_add_f32 v[78:79], v[78:79], v[88:89]
	s_waitcnt vmcnt(0)
	v_pk_add_f32 v[76:77], v[76:77], v[94:95]
	v_pk_add_f32 v[74:75], v[74:75], v[92:93]
	global_store_dwordx4 v[84:85], v[78:81], off
	global_store_dwordx4 v[84:85], v[74:77], off offset:16
	s_cbranch_vccnz .LBB0_1302
	v_mov_b32_e32 v88, v234
	v_mov_b32_e32 v89, v235
	v_mov_b32_e32 v90, v236
	v_mov_b32_e32 v91, v237
	v_mov_b32_e32 v92, v230
	v_mov_b32_e32 v93, v231
	v_mov_b32_e32 v94, v232
	v_mov_b32_e32 v95, v233
	v_pk_mul_f32 v[96:97], v[76:77], v[90:91]
	v_pk_mul_f32 v[92:93], v[78:79], v[92:93]
	v_pk_mul_f32 v[78:79], v[78:79], v[78:79]
	v_pk_mul_f32 v[94:95], v[80:81], v[94:95]
	v_pk_mul_f32 v[80:81], v[80:81], v[80:81]
	v_add_f32_e32 v78, v78, v79
	v_add_f32_e32 v78, v80, v78
	v_pk_mul_f32 v[90:91], v[74:75], v[88:89]
	v_pk_mul_f32 v[74:75], v[74:75], v[74:75]
	v_add_f32_e32 v78, v81, v78
	v_add_f32_e32 v74, v74, v78
	v_pk_mul_f32 v[76:77], v[76:77], v[76:77]
	v_add_f32_e32 v74, v75, v74
	v_add_f32_e32 v74, v76, v74
	v_add_f32_e32 v74, v77, v74
	v_cvt_pk_bf16_f32 v88, v92, v93
	v_cvt_pk_bf16_f32 v89, v94, v95
	v_cvt_pk_bf16_f32 v90, v90, v91
	v_cvt_pk_bf16_f32 v91, v96, v97
	global_store_dwordx4 v[82:83], v[88:91], off
	s_branch .LBB0_1303

.LBB0_1303:
	global_load_dwordx4 v[76:79], v[86:87], off offset:512 nt
	s_nop 0
	global_load_dwordx4 v[86:89], v[86:87], off offset:528 nt
	s_and_b64 vcc, exec, s[92:93]
	s_waitcnt vmcnt(1)
	v_pk_add_f32 v[72:73], v[72:73], v[78:79]
	v_pk_add_f32 v[70:71], v[70:71], v[76:77]
	s_waitcnt vmcnt(0)
	v_pk_add_f32 v[68:69], v[68:69], v[88:89]
	v_pk_add_f32 v[66:67], v[66:67], v[86:87]
	global_store_dwordx4 v[84:85], v[70:73], off offset:512
	global_store_dwordx4 v[84:85], v[66:69], off offset:528
	s_cbranch_vccnz .LBB0_1307
	v_mov_b32_e32 v76, v242
	v_mov_b32_e32 v77, v243
	v_mov_b32_e32 v78, v244
	v_mov_b32_e32 v79, v245
	v_mov_b32_e32 v84, v238
	v_mov_b32_e32 v85, v239
	v_mov_b32_e32 v86, v240
	v_mov_b32_e32 v87, v241
	v_pk_mul_f32 v[84:85], v[70:71], v[84:85]
	v_mul_f32_e32 v71, v71, v71
	v_fmac_f32_e32 v71, v70, v70
	v_fmac_f32_e32 v71, v72, v72
	v_fmac_f32_e32 v71, v73, v73
	v_fmac_f32_e32 v71, v66, v66
	v_fmac_f32_e32 v71, v67, v67
	v_pk_mul_f32 v[80:81], v[72:73], v[86:87]
	v_pk_mul_f32 v[86:87], v[68:69], v[78:79]
	v_fmac_f32_e32 v71, v68, v68
	v_and_b32_e32 v68, 64, v200
	v_pk_mul_f32 v[78:79], v[66:67], v[76:77]
	v_xor_b32_e32 v67, 16, v200
	v_add_u32_e32 v68, 64, v68
	v_cmp_lt_i32_e32 vcc, v67, v68
	v_fmac_f32_e32 v71, v69, v69
	v_add_f32_e32 v66, v74, v71
	v_cndmask_b32_e32 v67, v200, v67, vcc
	v_lshlrev_b32_e32 v67, 2, v67
	ds_bpermute_b32 v67, v67, v66
	v_cvt_pk_bf16_f32 v76, v84, v85
	v_cvt_pk_bf16_f32 v77, v80, v81
	v_cvt_pk_bf16_f32 v78, v78, v79
	v_cvt_pk_bf16_f32 v79, v86, v87
	s_waitcnt lgkmcnt(0)
	v_add_f32_e32 v66, v66, v67
	v_xor_b32_e32 v67, 32, v200
	v_cmp_lt_i32_e32 vcc, v67, v68
	global_store_dwordx4 v[82:83], v[76:79], off offset:256
	s_nop 0
	v_cndmask_b32_e32 v67, v200, v67, vcc
	v_lshlrev_b32_e32 v67, 2, v67
	ds_bpermute_b32 v67, v67, v66
	s_and_saveexec_b64 s[22:23], s[90:91]
	s_cbranch_execz .LBB0_1306
	v_lshl_add_u64 v[68:69], v[140:141], 2, s[8:9]
	s_waitcnt lgkmcnt(0)
	v_add_f32_e32 v66, v66, v67
	global_atomic_add_f32 v[68:69], v66, off offset:192

.LBB0_1307:
	s_mov_b64 s[22:23], 0x40000
	s_waitcnt lgkmcnt(0)
	v_lshl_add_u64 v[66:67], v[144:145], 0, s[22:23]
	v_lshlrev_b64 v[68:69], 2, v[66:67]
	v_lshl_add_u64 v[70:71], s[0:1], 0, v[68:69]
	global_load_dwordx4 v[72:75], v[70:71], off nt
	global_load_dwordx4 v[76:79], v[70:71], off offset:16 nt
	s_and_b64 vcc, exec, s[92:93]
	v_lshl_add_u64 v[68:69], s[10:11], 0, v[68:69]
	v_lshl_add_u64 v[66:67], v[66:67], 1, s[6:7]
	s_waitcnt vmcnt(1)
	v_pk_add_f32 v[64:65], v[64:65], v[74:75]
	v_pk_add_f32 v[62:63], v[62:63], v[72:73]
	s_waitcnt vmcnt(0)
	v_pk_add_f32 v[60:61], v[60:61], v[78:79]
	v_pk_add_f32 v[58:59], v[58:59], v[76:77]
	global_store_dwordx4 v[68:69], v[62:65], off
	global_store_dwordx4 v[68:69], v[58:61], off offset:16
	s_cbranch_vccnz .LBB0_1309
	v_mov_b32_e32 v72, v234
	v_mov_b32_e32 v73, v235
	v_mov_b32_e32 v74, v236
	v_mov_b32_e32 v75, v237
	v_mov_b32_e32 v76, v230
	v_mov_b32_e32 v77, v231
	v_mov_b32_e32 v78, v232
	v_mov_b32_e32 v79, v233
	v_pk_mul_f32 v[80:81], v[60:61], v[74:75]
	v_pk_mul_f32 v[76:77], v[62:63], v[76:77]
	v_pk_mul_f32 v[62:63], v[62:63], v[62:63]
	v_pk_mul_f32 v[78:79], v[64:65], v[78:79]
	v_pk_mul_f32 v[64:65], v[64:65], v[64:65]
	v_add_f32_e32 v62, v62, v63
	v_add_f32_e32 v62, v64, v62
	v_pk_mul_f32 v[74:75], v[58:59], v[72:73]
	v_pk_mul_f32 v[58:59], v[58:59], v[58:59]
	v_add_f32_e32 v62, v65, v62
	v_add_f32_e32 v58, v58, v62
	v_pk_mul_f32 v[60:61], v[60:61], v[60:61]
	v_add_f32_e32 v58, v59, v58
	v_add_f32_e32 v58, v60, v58
	v_add_f32_e32 v58, v61, v58
	v_cvt_pk_bf16_f32 v72, v76, v77
	v_cvt_pk_bf16_f32 v73, v78, v79
	v_cvt_pk_bf16_f32 v74, v74, v75
	v_cvt_pk_bf16_f32 v75, v80, v81
	global_store_dwordx4 v[66:67], v[72:75], off
	s_branch .LBB0_1310

.LBB0_1310:
	global_load_dwordx4 v[60:63], v[70:71], off offset:512 nt
	s_nop 0
	global_load_dwordx4 v[70:73], v[70:71], off offset:528 nt
	s_and_b64 vcc, exec, s[92:93]
	s_waitcnt vmcnt(1)
	v_pk_add_f32 v[56:57], v[56:57], v[62:63]
	v_pk_add_f32 v[54:55], v[54:55], v[60:61]
	s_waitcnt vmcnt(0)
	v_pk_add_f32 v[52:53], v[52:53], v[72:73]
	v_pk_add_f32 v[50:51], v[50:51], v[70:71]
	global_store_dwordx4 v[68:69], v[54:57], off offset:512
	global_store_dwordx4 v[68:69], v[50:53], off offset:528
	s_cbranch_vccnz .LBB0_1314
	v_mov_b32_e32 v60, v242
	v_mov_b32_e32 v61, v243
	v_mov_b32_e32 v62, v244
	v_mov_b32_e32 v63, v245
	v_mov_b32_e32 v68, v238
	v_mov_b32_e32 v69, v239
	v_mov_b32_e32 v70, v240
	v_mov_b32_e32 v71, v241
	v_pk_mul_f32 v[68:69], v[54:55], v[68:69]
	v_mul_f32_e32 v55, v55, v55
	v_fmac_f32_e32 v55, v54, v54
	v_fmac_f32_e32 v55, v56, v56
	v_fmac_f32_e32 v55, v57, v57
	v_fmac_f32_e32 v55, v50, v50
	v_fmac_f32_e32 v55, v51, v51
	v_pk_mul_f32 v[64:65], v[56:57], v[70:71]
	v_pk_mul_f32 v[70:71], v[52:53], v[62:63]
	v_fmac_f32_e32 v55, v52, v52
	v_and_b32_e32 v52, 64, v200
	v_pk_mul_f32 v[62:63], v[50:51], v[60:61]
	v_xor_b32_e32 v51, 16, v200
	v_add_u32_e32 v52, 64, v52
	v_cmp_lt_i32_e32 vcc, v51, v52
	v_fmac_f32_e32 v55, v53, v53
	v_add_f32_e32 v50, v58, v55
	v_cndmask_b32_e32 v51, v200, v51, vcc
	v_lshlrev_b32_e32 v51, 2, v51
	ds_bpermute_b32 v51, v51, v50
	v_cvt_pk_bf16_f32 v60, v68, v69
	v_cvt_pk_bf16_f32 v61, v64, v65
	v_cvt_pk_bf16_f32 v62, v62, v63
	v_cvt_pk_bf16_f32 v63, v70, v71
	s_waitcnt lgkmcnt(0)
	v_add_f32_e32 v50, v50, v51
	v_xor_b32_e32 v51, 32, v200
	v_cmp_lt_i32_e32 vcc, v51, v52
	global_store_dwordx4 v[66:67], v[60:63], off offset:256
	s_nop 0
	v_cndmask_b32_e32 v51, v200, v51, vcc
	v_lshlrev_b32_e32 v51, 2, v51
	ds_bpermute_b32 v51, v51, v50
	s_and_saveexec_b64 s[22:23], s[90:91]
	s_cbranch_execz .LBB0_1313
	v_lshl_add_u64 v[52:53], v[140:141], 2, s[8:9]
	s_waitcnt lgkmcnt(0)
	v_add_f32_e32 v50, v50, v51
	global_atomic_add_f32 v[52:53], v50, off offset:512

.LBB0_1314:
	s_mov_b64 s[22:23], 0x48000
	s_waitcnt lgkmcnt(0)
	v_lshl_add_u64 v[50:51], v[144:145], 0, s[22:23]
	v_lshlrev_b64 v[52:53], 2, v[50:51]
	v_lshl_add_u64 v[54:55], s[0:1], 0, v[52:53]
	global_load_dwordx4 v[56:59], v[54:55], off nt
	global_load_dwordx4 v[60:63], v[54:55], off offset:16 nt
	s_and_b64 vcc, exec, s[92:93]
	v_lshl_add_u64 v[52:53], s[10:11], 0, v[52:53]
	v_lshl_add_u64 v[50:51], v[50:51], 1, s[6:7]
	s_waitcnt vmcnt(1)
	v_pk_add_f32 v[48:49], v[48:49], v[58:59]
	v_pk_add_f32 v[46:47], v[46:47], v[56:57]
	s_waitcnt vmcnt(0)
	v_pk_add_f32 v[44:45], v[44:45], v[62:63]
	v_pk_add_f32 v[42:43], v[42:43], v[60:61]
	global_store_dwordx4 v[52:53], v[46:49], off
	global_store_dwordx4 v[52:53], v[42:45], off offset:16
	s_cbranch_vccnz .LBB0_1316
	v_mov_b32_e32 v56, v234
	v_mov_b32_e32 v57, v235
	v_mov_b32_e32 v58, v236
	v_mov_b32_e32 v59, v237
	v_mov_b32_e32 v60, v230
	v_mov_b32_e32 v61, v231
	v_mov_b32_e32 v62, v232
	v_mov_b32_e32 v63, v233
	v_pk_mul_f32 v[64:65], v[44:45], v[58:59]
	v_pk_mul_f32 v[60:61], v[46:47], v[60:61]
	v_pk_mul_f32 v[46:47], v[46:47], v[46:47]
	v_pk_mul_f32 v[62:63], v[48:49], v[62:63]
	v_pk_mul_f32 v[48:49], v[48:49], v[48:49]
	v_add_f32_e32 v46, v46, v47
	v_add_f32_e32 v46, v48, v46
	v_pk_mul_f32 v[58:59], v[42:43], v[56:57]
	v_pk_mul_f32 v[42:43], v[42:43], v[42:43]
	v_add_f32_e32 v46, v49, v46
	v_add_f32_e32 v42, v42, v46
	v_pk_mul_f32 v[44:45], v[44:45], v[44:45]
	v_add_f32_e32 v42, v43, v42
	v_add_f32_e32 v42, v44, v42
	v_add_f32_e32 v42, v45, v42
	v_cvt_pk_bf16_f32 v56, v60, v61
	v_cvt_pk_bf16_f32 v57, v62, v63
	v_cvt_pk_bf16_f32 v58, v58, v59
	v_cvt_pk_bf16_f32 v59, v64, v65
	global_store_dwordx4 v[50:51], v[56:59], off
	s_branch .LBB0_1317

.LBB0_1317:
	global_load_dwordx4 v[44:47], v[54:55], off offset:512 nt
	s_nop 0
	global_load_dwordx4 v[54:57], v[54:55], off offset:528 nt
	s_and_b64 vcc, exec, s[92:93]
	s_waitcnt vmcnt(1)
	v_pk_add_f32 v[40:41], v[40:41], v[46:47]
	v_pk_add_f32 v[38:39], v[38:39], v[44:45]
	s_waitcnt vmcnt(0)
	v_pk_add_f32 v[36:37], v[36:37], v[56:57]
	v_pk_add_f32 v[34:35], v[34:35], v[54:55]
	global_store_dwordx4 v[52:53], v[38:41], off offset:512
	global_store_dwordx4 v[52:53], v[34:37], off offset:528
	s_cbranch_vccnz .LBB0_1321
	v_mov_b32_e32 v44, v242
	v_mov_b32_e32 v45, v243
	v_mov_b32_e32 v46, v244
	v_mov_b32_e32 v47, v245
	v_mov_b32_e32 v52, v238
	v_mov_b32_e32 v53, v239
	v_mov_b32_e32 v54, v240
	v_mov_b32_e32 v55, v241
	v_pk_mul_f32 v[52:53], v[38:39], v[52:53]
	v_mul_f32_e32 v39, v39, v39
	v_fmac_f32_e32 v39, v38, v38
	v_fmac_f32_e32 v39, v40, v40
	v_fmac_f32_e32 v39, v41, v41
	v_fmac_f32_e32 v39, v34, v34
	v_fmac_f32_e32 v39, v35, v35
	v_pk_mul_f32 v[48:49], v[40:41], v[54:55]
	v_pk_mul_f32 v[54:55], v[36:37], v[46:47]
	v_fmac_f32_e32 v39, v36, v36
	v_and_b32_e32 v36, 64, v200
	v_pk_mul_f32 v[46:47], v[34:35], v[44:45]
	v_xor_b32_e32 v35, 16, v200
	v_add_u32_e32 v36, 64, v36
	v_cmp_lt_i32_e32 vcc, v35, v36
	v_fmac_f32_e32 v39, v37, v37
	v_add_f32_e32 v34, v42, v39
	v_cndmask_b32_e32 v35, v200, v35, vcc
	v_lshlrev_b32_e32 v35, 2, v35
	ds_bpermute_b32 v35, v35, v34
	v_cvt_pk_bf16_f32 v44, v52, v53
	v_cvt_pk_bf16_f32 v45, v48, v49
	v_cvt_pk_bf16_f32 v46, v46, v47
	v_cvt_pk_bf16_f32 v47, v54, v55
	s_waitcnt lgkmcnt(0)
	v_add_f32_e32 v34, v34, v35
	v_xor_b32_e32 v35, 32, v200
	v_cmp_lt_i32_e32 vcc, v35, v36
	global_store_dwordx4 v[50:51], v[44:47], off offset:256
	s_nop 0
	v_cndmask_b32_e32 v35, v200, v35, vcc
	v_lshlrev_b32_e32 v35, 2, v35
	ds_bpermute_b32 v35, v35, v34
	s_and_saveexec_b64 s[22:23], s[90:91]
	s_cbranch_execz .LBB0_1320
	v_lshl_add_u64 v[36:37], v[140:141], 2, s[8:9]
	s_waitcnt lgkmcnt(0)
	v_add_f32_e32 v34, v34, v35
	global_atomic_add_f32 v[36:37], v34, off offset:576

.LBB0_1321:
	s_mov_b64 s[22:23], 0x50000
	s_waitcnt lgkmcnt(0)
	v_lshl_add_u64 v[34:35], v[144:145], 0, s[22:23]
	v_lshlrev_b64 v[36:37], 2, v[34:35]
	v_lshl_add_u64 v[38:39], s[0:1], 0, v[36:37]
	global_load_dwordx4 v[40:43], v[38:39], off nt
	global_load_dwordx4 v[44:47], v[38:39], off offset:16 nt
	s_and_b64 vcc, exec, s[92:93]
	v_lshl_add_u64 v[36:37], s[10:11], 0, v[36:37]
	v_lshl_add_u64 v[34:35], v[34:35], 1, s[6:7]
	s_waitcnt vmcnt(1)
	v_pk_add_f32 v[32:33], v[32:33], v[42:43]
	v_pk_add_f32 v[30:31], v[30:31], v[40:41]
	s_waitcnt vmcnt(0)
	v_pk_add_f32 v[28:29], v[28:29], v[46:47]
	v_pk_add_f32 v[26:27], v[26:27], v[44:45]
	global_store_dwordx4 v[36:37], v[30:33], off
	global_store_dwordx4 v[36:37], v[26:29], off offset:16
	s_cbranch_vccnz .LBB0_1323
	v_mov_b32_e32 v40, v234
	v_mov_b32_e32 v41, v235
	v_mov_b32_e32 v42, v236
	v_mov_b32_e32 v43, v237
	v_mov_b32_e32 v44, v230
	v_mov_b32_e32 v45, v231
	v_mov_b32_e32 v46, v232
	v_mov_b32_e32 v47, v233
	v_pk_mul_f32 v[48:49], v[28:29], v[42:43]
	v_pk_mul_f32 v[44:45], v[30:31], v[44:45]
	v_pk_mul_f32 v[30:31], v[30:31], v[30:31]
	v_pk_mul_f32 v[46:47], v[32:33], v[46:47]
	v_pk_mul_f32 v[32:33], v[32:33], v[32:33]
	v_add_f32_e32 v30, v30, v31
	v_add_f32_e32 v30, v32, v30
	v_pk_mul_f32 v[42:43], v[26:27], v[40:41]
	v_pk_mul_f32 v[26:27], v[26:27], v[26:27]
	v_add_f32_e32 v30, v33, v30
	v_add_f32_e32 v26, v26, v30
	v_pk_mul_f32 v[28:29], v[28:29], v[28:29]
	v_add_f32_e32 v26, v27, v26
	v_add_f32_e32 v26, v28, v26
	v_add_f32_e32 v26, v29, v26
	v_cvt_pk_bf16_f32 v40, v44, v45
	v_cvt_pk_bf16_f32 v41, v46, v47
	v_cvt_pk_bf16_f32 v42, v42, v43
	v_cvt_pk_bf16_f32 v43, v48, v49
	global_store_dwordx4 v[34:35], v[40:43], off
	s_branch .LBB0_1324

.LBB0_1324:
	global_load_dwordx4 v[28:31], v[38:39], off offset:512 nt
	s_nop 0
	global_load_dwordx4 v[38:41], v[38:39], off offset:528 nt
	s_and_b64 vcc, exec, s[92:93]
	s_waitcnt vmcnt(1)
	v_pk_add_f32 v[24:25], v[24:25], v[30:31]
	v_pk_add_f32 v[22:23], v[22:23], v[28:29]
	s_waitcnt vmcnt(0)
	v_pk_add_f32 v[20:21], v[20:21], v[40:41]
	v_pk_add_f32 v[18:19], v[18:19], v[38:39]
	global_store_dwordx4 v[36:37], v[22:25], off offset:512
	global_store_dwordx4 v[36:37], v[18:21], off offset:528
	s_cbranch_vccnz .LBB0_1328
	v_mov_b32_e32 v28, v242
	v_mov_b32_e32 v29, v243
	v_mov_b32_e32 v30, v244
	v_mov_b32_e32 v31, v245
	v_mov_b32_e32 v36, v238
	v_mov_b32_e32 v37, v239
	v_mov_b32_e32 v38, v240
	v_mov_b32_e32 v39, v241
	v_pk_mul_f32 v[36:37], v[22:23], v[36:37]
	v_mul_f32_e32 v23, v23, v23
	v_fmac_f32_e32 v23, v22, v22
	v_fmac_f32_e32 v23, v24, v24
	v_fmac_f32_e32 v23, v25, v25
	v_fmac_f32_e32 v23, v18, v18
	v_fmac_f32_e32 v23, v19, v19
	v_pk_mul_f32 v[32:33], v[24:25], v[38:39]
	v_pk_mul_f32 v[38:39], v[20:21], v[30:31]
	v_fmac_f32_e32 v23, v20, v20
	v_and_b32_e32 v20, 64, v200
	v_pk_mul_f32 v[30:31], v[18:19], v[28:29]
	v_xor_b32_e32 v19, 16, v200
	v_add_u32_e32 v20, 64, v20
	v_cmp_lt_i32_e32 vcc, v19, v20
	v_fmac_f32_e32 v23, v21, v21
	v_add_f32_e32 v18, v26, v23
	v_cndmask_b32_e32 v19, v200, v19, vcc
	v_lshlrev_b32_e32 v19, 2, v19
	ds_bpermute_b32 v19, v19, v18
	v_cvt_pk_bf16_f32 v28, v36, v37
	v_cvt_pk_bf16_f32 v29, v32, v33
	v_cvt_pk_bf16_f32 v30, v30, v31
	v_cvt_pk_bf16_f32 v31, v38, v39
	s_waitcnt lgkmcnt(0)
	v_add_f32_e32 v18, v18, v19
	v_xor_b32_e32 v19, 32, v200
	v_cmp_lt_i32_e32 vcc, v19, v20
	global_store_dwordx4 v[34:35], v[28:31], off offset:256
	s_nop 0
	v_cndmask_b32_e32 v19, v200, v19, vcc
	v_lshlrev_b32_e32 v19, 2, v19
	ds_bpermute_b32 v19, v19, v18
	s_and_saveexec_b64 s[22:23], s[90:91]
	s_cbranch_execz .LBB0_1327
	v_lshl_add_u64 v[20:21], v[140:141], 2, s[8:9]
	s_waitcnt lgkmcnt(0)
	v_add_f32_e32 v18, v18, v19
	global_atomic_add_f32 v[20:21], v18, off offset:640

.LBB0_1328:
	s_mov_b64 s[22:23], 0x58000
	s_waitcnt lgkmcnt(0)
	v_lshl_add_u64 v[18:19], v[144:145], 0, s[22:23]
	v_lshlrev_b64 v[20:21], 2, v[18:19]
	v_lshl_add_u64 v[22:23], s[0:1], 0, v[20:21]
	global_load_dwordx4 v[24:27], v[22:23], off nt
	global_load_dwordx4 v[28:31], v[22:23], off offset:16 nt
	s_and_b64 vcc, exec, s[92:93]
	v_lshl_add_u64 v[20:21], s[10:11], 0, v[20:21]
	v_lshl_add_u64 v[18:19], v[18:19], 1, s[6:7]
	s_waitcnt vmcnt(1)
	v_pk_add_f32 v[16:17], v[16:17], v[26:27]
	v_pk_add_f32 v[14:15], v[14:15], v[24:25]
	s_waitcnt vmcnt(0)
	v_pk_add_f32 v[12:13], v[12:13], v[30:31]
	v_pk_add_f32 v[10:11], v[10:11], v[28:29]
	global_store_dwordx4 v[20:21], v[14:17], off
	global_store_dwordx4 v[20:21], v[10:13], off offset:16
	s_cbranch_vccnz .LBB0_1330
	v_mov_b32_e32 v24, v234
	v_mov_b32_e32 v25, v235
	v_mov_b32_e32 v26, v236
	v_mov_b32_e32 v27, v237
	v_mov_b32_e32 v28, v230
	v_mov_b32_e32 v29, v231
	v_mov_b32_e32 v30, v232
	v_mov_b32_e32 v31, v233
	v_pk_mul_f32 v[32:33], v[12:13], v[26:27]
	v_pk_mul_f32 v[28:29], v[14:15], v[28:29]
	v_pk_mul_f32 v[14:15], v[14:15], v[14:15]
	v_pk_mul_f32 v[30:31], v[16:17], v[30:31]
	v_pk_mul_f32 v[16:17], v[16:17], v[16:17]
	v_add_f32_e32 v14, v14, v15
	v_add_f32_e32 v14, v16, v14
	v_pk_mul_f32 v[26:27], v[10:11], v[24:25]
	v_pk_mul_f32 v[10:11], v[10:11], v[10:11]
	v_add_f32_e32 v14, v17, v14
	v_add_f32_e32 v10, v10, v14
	v_pk_mul_f32 v[12:13], v[12:13], v[12:13]
	v_add_f32_e32 v10, v11, v10
	v_add_f32_e32 v10, v12, v10
	v_add_f32_e32 v10, v13, v10
	v_cvt_pk_bf16_f32 v24, v28, v29
	v_cvt_pk_bf16_f32 v25, v30, v31
	v_cvt_pk_bf16_f32 v26, v26, v27
	v_cvt_pk_bf16_f32 v27, v32, v33
	global_store_dwordx4 v[18:19], v[24:27], off
	s_branch .LBB0_1331

.LBB0_1331:
	global_load_dwordx4 v[12:15], v[22:23], off offset:512 nt
	s_nop 0
	global_load_dwordx4 v[22:25], v[22:23], off offset:528 nt
	s_and_b64 vcc, exec, s[92:93]
	s_waitcnt vmcnt(1)
	v_pk_add_f32 v[8:9], v[8:9], v[14:15]
	v_pk_add_f32 v[6:7], v[6:7], v[12:13]
	s_waitcnt vmcnt(0)
	v_pk_add_f32 v[4:5], v[4:5], v[24:25]
	v_pk_add_f32 v[2:3], v[2:3], v[22:23]
	global_store_dwordx4 v[20:21], v[6:9], off offset:512
	global_store_dwordx4 v[20:21], v[2:5], off offset:528
	s_cbranch_vccnz .LBB0_1335
	v_mov_b32_e32 v12, v242
	v_mov_b32_e32 v13, v243
	v_mov_b32_e32 v14, v244
	v_mov_b32_e32 v15, v245
	v_mov_b32_e32 v20, v238
	v_mov_b32_e32 v21, v239
	v_mov_b32_e32 v22, v240
	v_mov_b32_e32 v23, v241
	v_pk_mul_f32 v[20:21], v[6:7], v[20:21]
	v_mul_f32_e32 v7, v7, v7
	v_fmac_f32_e32 v7, v6, v6
	v_fmac_f32_e32 v7, v8, v8
	v_fmac_f32_e32 v7, v9, v9
	v_fmac_f32_e32 v7, v2, v2
	v_fmac_f32_e32 v7, v3, v3
	v_pk_mul_f32 v[16:17], v[8:9], v[22:23]
	v_pk_mul_f32 v[22:23], v[4:5], v[14:15]
	v_fmac_f32_e32 v7, v4, v4
	v_and_b32_e32 v4, 64, v200
	v_pk_mul_f32 v[14:15], v[2:3], v[12:13]
	v_xor_b32_e32 v3, 16, v200
	v_add_u32_e32 v4, 64, v4
	v_cmp_lt_i32_e32 vcc, v3, v4
	v_fmac_f32_e32 v7, v5, v5
	v_add_f32_e32 v2, v10, v7
	v_cndmask_b32_e32 v3, v200, v3, vcc
	v_lshlrev_b32_e32 v3, 2, v3
	ds_bpermute_b32 v3, v3, v2
	v_cvt_pk_bf16_f32 v12, v20, v21
	v_cvt_pk_bf16_f32 v13, v16, v17
	v_cvt_pk_bf16_f32 v14, v14, v15
	v_cvt_pk_bf16_f32 v15, v22, v23
	s_waitcnt lgkmcnt(0)
	v_add_f32_e32 v2, v2, v3
	v_xor_b32_e32 v3, 32, v200
	v_cmp_lt_i32_e32 vcc, v3, v4
	global_store_dwordx4 v[18:19], v[12:15], off offset:256
	s_nop 0
	v_cndmask_b32_e32 v3, v200, v3, vcc
	v_lshlrev_b32_e32 v3, 2, v3
	ds_bpermute_b32 v3, v3, v2
	s_and_saveexec_b64 s[22:23], s[90:91]
	s_cbranch_execz .LBB0_1334
	v_lshl_add_u64 v[4:5], v[140:141], 2, s[8:9]
	s_waitcnt lgkmcnt(0)
	v_add_f32_e32 v2, v2, v3
	global_atomic_add_f32 v[4:5], v2, off offset:704
